# v61 + MFMA segments of the GEMM K-loops run at s_setprio 3 instead of 1
# speedup vs baseline: 1.0059x; 1.0059x over previous
; #define PG8_STAGE(bufoff, gbase, voff) do { _Pragma("unroll") for (int _i = 0; _i < 2; ++_i) \
;         __builtin_amdgcn_global_load_lds((const unsigned*)((const char*)(gbase) + (voff)[_i]), (LAS unsigned*)(lds + (bufoff) + ldsw + _i * 8192), 16, 0, 0); } while (0)
; #define PG8_LDA(dst, b, h) do { _Pragma("unroll") for (int m = 0; m < 4; ++m) _Pragma("unroll") for (int k = 0; k < 2; ++k) dst[m][k] = *(const LAS bf16x8*)(lds + PG8_SA(b, h) + aoff + m * 2048 + k * 1024); } while (0)
; #define PG8_LDB(dst, b, h) do { _Pragma("unroll") for (int n = 0; n < 2; ++n) _Pragma("unroll") for (int k = 0; k < 2; ++k) dst[n][k] = *(const LAS bf16x8*)(lds + PG8_SB(b, h) + boff + n * 2048 + k * 1024); } while (0)
; #define PG8_MMA(ai, bj, At, Bt) do { __builtin_amdgcn_s_setprio(1); _Pragma("unroll") for (int m = 0; m < 4; ++m) _Pragma("unroll") for (int n = 0; n < 2; ++n) _Pragma("unroll") for (int k = 0; k < 2; ++k) \
;         acc[ai][bj][m][n] = __builtin_amdgcn_mfma_f32_16x16x32_bf16(Bt[n][k], At[m][k], acc[ai][bj][m][n], 0, 0, 0); __builtin_amdgcn_s_setprio(0); } while (0)
; #define PG8_WAIT_V(n) asm volatile("s_waitcnt vmcnt(" #n ")" ::: "memory")
; #define PG8_WAIT_L(n) asm volatile("s_waitcnt lgkmcnt(" #n ")" ::: "memory")
; #define PG8_BAR __builtin_amdgcn_s_barrier()
; template <class Epi, class Sched>
; __device__ __forceinline__ void gemm_phase(LAS unsigned char* lds, const Gemm g, const Sched& S, const Epi& E) {
;     ...
;         for (int t = 0; t < nt; t += 2) {
;             const bool last = (t == nt - 2);
;             const char* a1 = cA + (size_t)(t + 1) * kstep;
;             const char* a2 = last ? nA : cA + (size_t)(t + 2) * kstep; const char* b2 = last ? nB : cB + (size_t)(t + 2) * kstep;
;             const char* a3 = a2 + kstep; const char* b3 = b2 + kstep;
;             if (last && has_next) S.a_ready(nxt);
;             PG8_LDB(B0, 0, 0); PG8_LDB(B1, 0, 1); PG8_SCHED; PG8_LDA(At, 0, 0); PG8_STAGE(PG8_SA(1, 1), a1 + hstep, voffA);
;             PG8_WAIT_V(8); PG8_WAIT_L(0); PG8_BAR; PG8_MMA(0, 0, At, B0); PG8_MMA(0, 1, At, B1); PG8_BAR; PG8_SCHED;
;             PG8_LDA(At, 0, 1); PG8_STAGE(PG8_SB(0, 0), b2, voffB); PG8_STAGE(PG8_SB(0, 1), b2 + hstep, voffB); PG8_STAGE(PG8_SA(0, 0), a2, voffA);
;             PG8_WAIT_V(8); PG8_WAIT_L(0); PG8_BAR; PG8_MMA(1, 0, At, B0); PG8_MMA(1, 1, At, B1); PG8_BAR; PG8_SCHED;
.LBB0_131:
	s_add_i32 s58, s50, 2
	s_add_u32 s48, s46, 0x100
	s_addc_u32 s49, s47, 0
	s_add_u32 s1, s9, s46
	s_addc_u32 s51, s36, s47
	s_cmp_eq_u32 s56, s50
	s_cselect_b32 s50, 0, s48
	s_cselect_b32 s59, 0, s49
	s_cselect_b32 s60, s44, s1
	s_cselect_b32 s61, s45, s51
	s_add_u32 s50, s2, s50
	s_addc_u32 s51, s3, s59
	s_add_i32 s1, 0, 0x10000
	s_add_i32 s59, 0, 0x14000
	v_add_u32_e32 v156, s1, v142
	v_add_u32_e32 v172, s59, v142
	ds_read_b128 v[144:147], v156
	ds_read_b128 v[148:151], v156 offset:1024
	ds_read_b128 v[152:155], v156 offset:2048
	ds_read_b128 v[156:159], v156 offset:3072
	ds_read_b128 v[160:163], v172
	ds_read_b128 v[164:167], v172 offset:1024
	ds_read_b128 v[168:171], v172 offset:2048
	ds_read_b128 v[172:175], v172 offset:3072
	s_add_u32 s46, s46, s2
	s_addc_u32 s47, s47, s3
	s_add_u32 s46, s46, s20
	s_addc_u32 s47, s47, s21
	s_add_u32 s46, s46, 0x80
	s_addc_u32 s47, s47, 0
	s_add_i32 m0, s5, 0xc000
	ds_read_b128 v[176:179], v143
	ds_read_b128 v[180:183], v143 offset:1024
	ds_read_b128 v[184:187], v143 offset:2048
	ds_read_b128 v[192:195], v143 offset:3072
	ds_read_b128 v[196:199], v143 offset:4096
	ds_read_b128 v[200:203], v143 offset:5120
	ds_read_b128 v[204:207], v143 offset:6144
	ds_read_b128 v[208:211], v143 offset:7168
	global_load_lds_dwordx4 v134, s[46:47]
	s_add_i32 m0, s5, 0xe000
	s_nop 0
	global_load_lds_dwordx4 v132, s[46:47]
	s_waitcnt vmcnt(8)
	s_waitcnt lgkmcnt(0)
	s_barrier
	s_setprio 3
	s_waitcnt lgkmcnt(0)
	v_mfma_f32_16x16x32_bf16 v[122:125], v[144:147], v[176:179], v[122:125]
	v_mfma_f32_16x16x32_bf16 v[126:129], v[152:155], v[176:179], v[126:129]
	v_mfma_f32_16x16x32_bf16 v[110:113], v[144:147], v[184:187], v[110:113]
	v_mfma_f32_16x16x32_bf16 v[106:109], v[152:155], v[184:187], v[106:109]
	v_mfma_f32_16x16x32_bf16 v[94:97], v[144:147], v[196:199], v[94:97]
	v_mfma_f32_16x16x32_bf16 v[90:93], v[152:155], v[196:199], v[90:93]
	v_mfma_f32_16x16x32_bf16 v[78:81], v[144:147], v[204:207], v[78:81]
	v_mfma_f32_16x16x32_bf16 v[74:77], v[152:155], v[204:207], v[74:77]
	v_mfma_f32_16x16x32_bf16 v[122:125], v[148:151], v[180:183], v[122:125]
	v_mfma_f32_16x16x32_bf16 v[126:129], v[156:159], v[180:183], v[126:129]
	v_mfma_f32_16x16x32_bf16 v[110:113], v[148:151], v[192:195], v[110:113]
	v_mfma_f32_16x16x32_bf16 v[106:109], v[156:159], v[192:195], v[106:109]
	v_mfma_f32_16x16x32_bf16 v[94:97], v[148:151], v[200:203], v[94:97]
	v_mfma_f32_16x16x32_bf16 v[90:93], v[156:159], v[200:203], v[90:93]
	v_mfma_f32_16x16x32_bf16 v[78:81], v[148:151], v[208:211], v[78:81]
	v_mfma_f32_16x16x32_bf16 v[74:77], v[156:159], v[208:211], v[74:77]
	s_setprio 0
	s_setprio 3
	v_mfma_f32_16x16x32_bf16 v[118:121], v[160:163], v[176:179], v[118:121]
	v_mfma_f32_16x16x32_bf16 v[114:117], v[168:171], v[176:179], v[114:117]
	v_mfma_f32_16x16x32_bf16 v[102:105], v[160:163], v[184:187], v[102:105]
	v_mfma_f32_16x16x32_bf16 v[98:101], v[168:171], v[184:187], v[98:101]
	v_mfma_f32_16x16x32_bf16 v[86:89], v[160:163], v[196:199], v[86:89]
	v_mfma_f32_16x16x32_bf16 v[82:85], v[168:171], v[196:199], v[82:85]
	v_mfma_f32_16x16x32_bf16 v[70:73], v[160:163], v[204:207], v[70:73]
	v_mfma_f32_16x16x32_bf16 v[66:69], v[168:171], v[204:207], v[66:69]
	v_mfma_f32_16x16x32_bf16 v[118:121], v[164:167], v[180:183], v[118:121]
	v_mfma_f32_16x16x32_bf16 v[114:117], v[172:175], v[180:183], v[114:117]
	v_mfma_f32_16x16x32_bf16 v[102:105], v[164:167], v[192:195], v[102:105]
	v_mfma_f32_16x16x32_bf16 v[98:101], v[172:175], v[192:195], v[98:101]
	v_mfma_f32_16x16x32_bf16 v[86:89], v[164:167], v[200:203], v[86:89]
	v_mfma_f32_16x16x32_bf16 v[82:85], v[172:175], v[200:203], v[82:85]
	v_mfma_f32_16x16x32_bf16 v[70:73], v[164:167], v[208:211], v[70:73]
	v_mfma_f32_16x16x32_bf16 v[66:69], v[172:175], v[208:211], v[66:69]
	s_setprio 0
	s_barrier
	s_add_i32 s1, s1, s4
	s_mov_b32 m0, s1
	ds_read_b128 v[176:179], v143 offset:16384
	ds_read_b128 v[180:183], v143 offset:17408
	ds_read_b128 v[184:187], v143 offset:18432
	ds_read_b128 v[192:195], v143 offset:19456
	ds_read_b128 v[196:199], v143 offset:20480
	ds_read_b128 v[200:203], v143 offset:21504
	ds_read_b128 v[204:207], v143 offset:22528
	ds_read_b128 v[208:211], v143 offset:23552
	global_load_lds_dwordx4 v0, s[60:61]
	s_add_i32 m0, s1, 0x2000
	s_add_u32 s46, s60, s20
	s_addc_u32 s47, s61, s21
	s_add_i32 s1, s59, s4
	global_load_lds_dwordx4 v130, s[60:61]
	s_mov_b32 m0, s1
	s_nop 0
	global_load_lds_dwordx4 v0, s[46:47]
	s_add_i32 m0, s1, 0x2000
	s_nop 0
	global_load_lds_dwordx4 v130, s[46:47]
	s_mov_b32 m0, s5
	s_nop 0
	global_load_lds_dwordx4 v134, s[50:51]
	s_mov_b32 m0, s18
	s_nop 0
	global_load_lds_dwordx4 v132, s[50:51]
	s_waitcnt vmcnt(8)
	s_waitcnt lgkmcnt(0)
	s_barrier
; #define PG8_STAGE(bufoff, gbase, voff) do { _Pragma("unroll") for (int _i = 0; _i < 2; ++_i) \
;         __builtin_amdgcn_global_load_lds((const unsigned*)((const char*)(gbase) + (voff)[_i]), (LAS unsigned*)(lds + (bufoff) + ldsw + _i * 8192), 16, 0, 0); } while (0)
; #define PG8_LDA(dst, b, h) do { _Pragma("unroll") for (int m = 0; m < 4; ++m) _Pragma("unroll") for (int k = 0; k < 2; ++k) dst[m][k] = *(const LAS bf16x8*)(lds + PG8_SA(b, h) + aoff + m * 2048 + k * 1024); } while (0)
; #define PG8_LDB(dst, b, h) do { _Pragma("unroll") for (int n = 0; n < 2; ++n) _Pragma("unroll") for (int k = 0; k < 2; ++k) dst[n][k] = *(const LAS bf16x8*)(lds + PG8_SB(b, h) + boff + n * 2048 + k * 1024); } while (0)
; #define PG8_MMA(ai, bj, At, Bt) do { __builtin_amdgcn_s_setprio(1); _Pragma("unroll") for (int m = 0; m < 4; ++m) _Pragma("unroll") for (int n = 0; n < 2; ++n) _Pragma("unroll") for (int k = 0; k < 2; ++k) \
;         acc[ai][bj][m][n] = __builtin_amdgcn_mfma_f32_16x16x32_bf16(Bt[n][k], At[m][k], acc[ai][bj][m][n], 0, 0, 0); __builtin_amdgcn_s_setprio(0); } while (0)
; #define PG8_WAIT_V(n) asm volatile("s_waitcnt vmcnt(" #n ")" ::: "memory")
; #define PG8_WAIT_L(n) asm volatile("s_waitcnt lgkmcnt(" #n ")" ::: "memory")
; #define PG8_BAR __builtin_amdgcn_s_barrier()
; #define PG8_SCHED __builtin_amdgcn_sched_barrier(0)
; template <class Epi, class Sched>
; __device__ __forceinline__ void gemm_phase(LAS unsigned char* lds, const Gemm g, const Sched& S, const Epi& E) {
;     ...
;             PG8_WAIT_V(8); PG8_WAIT_L(0); PG8_BAR; PG8_MMA(1, 0, At, B0); PG8_MMA(1, 1, At, B1); PG8_BAR; PG8_SCHED;
;             PG8_LDB(B0, 1, 0); PG8_LDB(B1, 1, 1); PG8_SCHED; PG8_LDA(At, 1, 0); PG8_STAGE(PG8_SA(0, 1), a2 + hstep, voffA);
;             PG8_WAIT_V(8); PG8_WAIT_L(0); PG8_BAR; PG8_MMA(0, 0, At, B0); PG8_MMA(0, 1, At, B1); PG8_BAR; PG8_SCHED;
	s_setprio 3
	s_waitcnt lgkmcnt(0)
	v_mfma_f32_16x16x32_bf16 v[62:65], v[144:147], v[176:179], v[62:65]
	v_mfma_f32_16x16x32_bf16 v[58:61], v[152:155], v[176:179], v[58:61]
	v_mfma_f32_16x16x32_bf16 v[46:49], v[144:147], v[184:187], v[46:49]
	v_mfma_f32_16x16x32_bf16 v[42:45], v[152:155], v[184:187], v[42:45]
	v_mfma_f32_16x16x32_bf16 v[30:33], v[144:147], v[196:199], v[30:33]
	v_mfma_f32_16x16x32_bf16 v[26:29], v[152:155], v[196:199], v[26:29]
	v_mfma_f32_16x16x32_bf16 v[14:17], v[144:147], v[204:207], v[14:17]
	v_mfma_f32_16x16x32_bf16 v[10:13], v[152:155], v[204:207], v[10:13]
	v_mfma_f32_16x16x32_bf16 v[62:65], v[148:151], v[180:183], v[62:65]
	v_mfma_f32_16x16x32_bf16 v[58:61], v[156:159], v[180:183], v[58:61]
	v_mfma_f32_16x16x32_bf16 v[46:49], v[148:151], v[192:195], v[46:49]
	v_mfma_f32_16x16x32_bf16 v[42:45], v[156:159], v[192:195], v[42:45]
	v_mfma_f32_16x16x32_bf16 v[30:33], v[148:151], v[200:203], v[30:33]
	v_mfma_f32_16x16x32_bf16 v[26:29], v[156:159], v[200:203], v[26:29]
	v_mfma_f32_16x16x32_bf16 v[14:17], v[148:151], v[208:211], v[14:17]
	v_mfma_f32_16x16x32_bf16 v[10:13], v[156:159], v[208:211], v[10:13]
	s_setprio 0
	s_setprio 3
	v_mfma_f32_16x16x32_bf16 v[54:57], v[160:163], v[176:179], v[54:57]
	v_mfma_f32_16x16x32_bf16 v[50:53], v[168:171], v[176:179], v[50:53]
	v_mfma_f32_16x16x32_bf16 v[38:41], v[160:163], v[184:187], v[38:41]
	v_mfma_f32_16x16x32_bf16 v[34:37], v[168:171], v[184:187], v[34:37]
	v_mfma_f32_16x16x32_bf16 v[22:25], v[160:163], v[196:199], v[22:25]
	v_mfma_f32_16x16x32_bf16 v[18:21], v[168:171], v[196:199], v[18:21]
	v_mfma_f32_16x16x32_bf16 v[6:9], v[160:163], v[204:207], v[6:9]
	v_mfma_f32_16x16x32_bf16 v[2:5], v[168:171], v[204:207], v[2:5]
	v_mfma_f32_16x16x32_bf16 v[54:57], v[164:167], v[180:183], v[54:57]
	v_mfma_f32_16x16x32_bf16 v[50:53], v[172:175], v[180:183], v[50:53]
	v_mfma_f32_16x16x32_bf16 v[38:41], v[164:167], v[192:195], v[38:41]
	v_mfma_f32_16x16x32_bf16 v[34:37], v[172:175], v[192:195], v[34:37]
	v_mfma_f32_16x16x32_bf16 v[22:25], v[164:167], v[200:203], v[22:25]
	v_mfma_f32_16x16x32_bf16 v[18:21], v[172:175], v[200:203], v[18:21]
	v_mfma_f32_16x16x32_bf16 v[6:9], v[164:167], v[208:211], v[6:9]
	v_mfma_f32_16x16x32_bf16 v[2:5], v[172:175], v[208:211], v[2:5]
	s_setprio 0
	s_barrier
	s_add_i32 s1, 0, 0x18000
	s_add_i32 s59, 0, 0x1c000
	v_add_u32_e32 v156, s1, v142
	v_add_u32_e32 v172, s59, v142
	ds_read_b128 v[144:147], v156
	ds_read_b128 v[148:151], v156 offset:1024
	ds_read_b128 v[152:155], v156 offset:2048
	ds_read_b128 v[156:159], v156 offset:3072
	ds_read_b128 v[160:163], v172
	ds_read_b128 v[164:167], v172 offset:1024
	ds_read_b128 v[168:171], v172 offset:2048
	ds_read_b128 v[172:175], v172 offset:3072
	s_add_u32 s46, s50, s20
	s_addc_u32 s47, s51, s21
	s_mov_b32 m0, s19
	ds_read_b128 v[176:179], v143 offset:32768
	ds_read_b128 v[180:183], v143 offset:33792
	ds_read_b128 v[184:187], v143 offset:34816
	ds_read_b128 v[192:195], v143 offset:35840
	ds_read_b128 v[196:199], v143 offset:36864
	ds_read_b128 v[200:203], v143 offset:37888
	ds_read_b128 v[204:207], v143 offset:38912
	ds_read_b128 v[208:211], v143 offset:39936
	global_load_lds_dwordx4 v134, s[46:47]
	s_mov_b32 m0, s52
	s_nop 0
	global_load_lds_dwordx4 v132, s[46:47]
	s_waitcnt vmcnt(8)
	s_waitcnt lgkmcnt(0)
	s_barrier
	s_setprio 3
	s_waitcnt lgkmcnt(0)
	v_mfma_f32_16x16x32_bf16 v[122:125], v[144:147], v[176:179], v[122:125]
	v_mfma_f32_16x16x32_bf16 v[126:129], v[152:155], v[176:179], v[126:129]
	v_mfma_f32_16x16x32_bf16 v[110:113], v[144:147], v[184:187], v[110:113]
	v_mfma_f32_16x16x32_bf16 v[106:109], v[152:155], v[184:187], v[106:109]
	v_mfma_f32_16x16x32_bf16 v[94:97], v[144:147], v[196:199], v[94:97]
	v_mfma_f32_16x16x32_bf16 v[90:93], v[152:155], v[196:199], v[90:93]
	v_mfma_f32_16x16x32_bf16 v[78:81], v[144:147], v[204:207], v[78:81]
	v_mfma_f32_16x16x32_bf16 v[74:77], v[152:155], v[204:207], v[74:77]
	v_mfma_f32_16x16x32_bf16 v[122:125], v[148:151], v[180:183], v[122:125]
	v_mfma_f32_16x16x32_bf16 v[126:129], v[156:159], v[180:183], v[126:129]
	v_mfma_f32_16x16x32_bf16 v[110:113], v[148:151], v[192:195], v[110:113]
	v_mfma_f32_16x16x32_bf16 v[106:109], v[156:159], v[192:195], v[106:109]
	v_mfma_f32_16x16x32_bf16 v[94:97], v[148:151], v[200:203], v[94:97]
	v_mfma_f32_16x16x32_bf16 v[90:93], v[156:159], v[200:203], v[90:93]
	v_mfma_f32_16x16x32_bf16 v[78:81], v[148:151], v[208:211], v[78:81]
	v_mfma_f32_16x16x32_bf16 v[74:77], v[156:159], v[208:211], v[74:77]
	s_setprio 0
	s_setprio 3
	v_mfma_f32_16x16x32_bf16 v[118:121], v[160:163], v[176:179], v[118:121]
	v_mfma_f32_16x16x32_bf16 v[114:117], v[168:171], v[176:179], v[114:117]
	v_mfma_f32_16x16x32_bf16 v[102:105], v[160:163], v[184:187], v[102:105]
	v_mfma_f32_16x16x32_bf16 v[98:101], v[168:171], v[184:187], v[98:101]
	v_mfma_f32_16x16x32_bf16 v[86:89], v[160:163], v[196:199], v[86:89]
	v_mfma_f32_16x16x32_bf16 v[82:85], v[168:171], v[196:199], v[82:85]
	v_mfma_f32_16x16x32_bf16 v[70:73], v[160:163], v[204:207], v[70:73]
	v_mfma_f32_16x16x32_bf16 v[66:69], v[168:171], v[204:207], v[66:69]
	v_mfma_f32_16x16x32_bf16 v[118:121], v[164:167], v[180:183], v[118:121]
	v_mfma_f32_16x16x32_bf16 v[114:117], v[172:175], v[180:183], v[114:117]
	v_mfma_f32_16x16x32_bf16 v[102:105], v[164:167], v[192:195], v[102:105]
	v_mfma_f32_16x16x32_bf16 v[98:101], v[172:175], v[192:195], v[98:101]
	v_mfma_f32_16x16x32_bf16 v[86:89], v[164:167], v[200:203], v[86:89]
	v_mfma_f32_16x16x32_bf16 v[82:85], v[172:175], v[200:203], v[82:85]
	v_mfma_f32_16x16x32_bf16 v[70:73], v[164:167], v[208:211], v[70:73]
	v_mfma_f32_16x16x32_bf16 v[66:69], v[172:175], v[208:211], v[66:69]
	s_setprio 0
	s_barrier
; #define PG8_STAGE(bufoff, gbase, voff) do { _Pragma("unroll") for (int _i = 0; _i < 2; ++_i) \
;         __builtin_amdgcn_global_load_lds((const unsigned*)((const char*)(gbase) + (voff)[_i]), (LAS unsigned*)(lds + (bufoff) + ldsw + _i * 8192), 16, 0, 0); } while (0)
; #define PG8_LDA(dst, b, h) do { _Pragma("unroll") for (int m = 0; m < 4; ++m) _Pragma("unroll") for (int k = 0; k < 2; ++k) dst[m][k] = *(const LAS bf16x8*)(lds + PG8_SA(b, h) + aoff + m * 2048 + k * 1024); } while (0)
; #define PG8_MMA(ai, bj, At, Bt) do { __builtin_amdgcn_s_setprio(1); _Pragma("unroll") for (int m = 0; m < 4; ++m) _Pragma("unroll") for (int n = 0; n < 2; ++n) _Pragma("unroll") for (int k = 0; k < 2; ++k) \
;         acc[ai][bj][m][n] = __builtin_amdgcn_mfma_f32_16x16x32_bf16(Bt[n][k], At[m][k], acc[ai][bj][m][n], 0, 0, 0); __builtin_amdgcn_s_setprio(0); } while (0)
; #define PG8_WAIT_V(n) asm volatile("s_waitcnt vmcnt(" #n ")" ::: "memory")
; #define PG8_WAIT_L(n) asm volatile("s_waitcnt lgkmcnt(" #n ")" ::: "memory")
; #define PG8_BAR __builtin_amdgcn_s_barrier()
; #define PG8_SCHED __builtin_amdgcn_sched_barrier(0)
; template <class Epi, class Sched>
; __device__ __forceinline__ void gemm_phase(LAS unsigned char* lds, const Gemm g, const Sched& S, const Epi& E) {
;     ...
;             PG8_LDA(At, 1, 1); PG8_STAGE(PG8_SB(1, 0), b3, voffB); PG8_STAGE(PG8_SB(1, 1), b3 + hstep, voffB); PG8_STAGE(PG8_SA(1, 0), a3, voffA);
;             PG8_WAIT_V(8); PG8_WAIT_L(0); PG8_BAR; PG8_MMA(1, 0, At, B0); PG8_MMA(1, 1, At, B1); PG8_BAR; PG8_SCHED;
;         }
	s_add_i32 s1, s1, s4
	s_add_u32 s46, s60, 0x80
	s_addc_u32 s47, s61, 0
	s_mov_b32 m0, s1
	ds_read_b128 v[176:179], v143 offset:49152
	ds_read_b128 v[180:183], v143 offset:50176
	ds_read_b128 v[184:187], v143 offset:51200
	ds_read_b128 v[192:195], v143 offset:52224
	ds_read_b128 v[196:199], v143 offset:53248
	ds_read_b128 v[200:203], v143 offset:54272
	ds_read_b128 v[204:207], v143 offset:55296
	ds_read_b128 v[208:211], v143 offset:56320
	global_load_lds_dwordx4 v0, s[46:47]
	s_add_i32 m0, s1, 0x2000
	s_add_i32 s1, s59, s4
	global_load_lds_dwordx4 v130, s[46:47]
	s_add_u32 s46, s46, s20
	s_addc_u32 s47, s47, s21
	s_mov_b32 m0, s1
	s_nop 0
	global_load_lds_dwordx4 v0, s[46:47]
	s_add_i32 m0, s1, 0x2000
	s_nop 0
	global_load_lds_dwordx4 v130, s[46:47]
	s_add_u32 s46, s50, 0x80
	s_addc_u32 s47, s51, 0
	s_mov_b32 m0, s53
	s_nop 0
	global_load_lds_dwordx4 v134, s[46:47]
	s_mov_b32 m0, s54
	s_nop 0
	global_load_lds_dwordx4 v132, s[46:47]
	s_waitcnt vmcnt(8)
	s_waitcnt lgkmcnt(0)
	s_barrier
	s_setprio 3
	s_waitcnt lgkmcnt(0)
	v_mfma_f32_16x16x32_bf16 v[62:65], v[144:147], v[176:179], v[62:65]
	v_mfma_f32_16x16x32_bf16 v[58:61], v[152:155], v[176:179], v[58:61]
	v_mfma_f32_16x16x32_bf16 v[46:49], v[144:147], v[184:187], v[46:49]
	v_mfma_f32_16x16x32_bf16 v[42:45], v[152:155], v[184:187], v[42:45]
	v_mfma_f32_16x16x32_bf16 v[30:33], v[144:147], v[196:199], v[30:33]
	v_mfma_f32_16x16x32_bf16 v[26:29], v[152:155], v[196:199], v[26:29]
	v_mfma_f32_16x16x32_bf16 v[14:17], v[144:147], v[204:207], v[14:17]
	v_mfma_f32_16x16x32_bf16 v[10:13], v[152:155], v[204:207], v[10:13]
	v_mfma_f32_16x16x32_bf16 v[62:65], v[148:151], v[180:183], v[62:65]
	v_mfma_f32_16x16x32_bf16 v[58:61], v[156:159], v[180:183], v[58:61]
	v_mfma_f32_16x16x32_bf16 v[46:49], v[148:151], v[192:195], v[46:49]
	v_mfma_f32_16x16x32_bf16 v[42:45], v[156:159], v[192:195], v[42:45]
	v_mfma_f32_16x16x32_bf16 v[30:33], v[148:151], v[200:203], v[30:33]
	v_mfma_f32_16x16x32_bf16 v[26:29], v[156:159], v[200:203], v[26:29]
	v_mfma_f32_16x16x32_bf16 v[14:17], v[148:151], v[208:211], v[14:17]
	v_mfma_f32_16x16x32_bf16 v[10:13], v[156:159], v[208:211], v[10:13]
	s_setprio 0
	s_setprio 3
	v_mfma_f32_16x16x32_bf16 v[54:57], v[160:163], v[176:179], v[54:57]
	v_mfma_f32_16x16x32_bf16 v[50:53], v[168:171], v[176:179], v[50:53]
	v_mfma_f32_16x16x32_bf16 v[38:41], v[160:163], v[184:187], v[38:41]
	v_mfma_f32_16x16x32_bf16 v[34:37], v[168:171], v[184:187], v[34:37]
	v_mfma_f32_16x16x32_bf16 v[22:25], v[160:163], v[196:199], v[22:25]
	v_mfma_f32_16x16x32_bf16 v[18:21], v[168:171], v[196:199], v[18:21]
	v_mfma_f32_16x16x32_bf16 v[6:9], v[160:163], v[204:207], v[6:9]
	v_mfma_f32_16x16x32_bf16 v[2:5], v[168:171], v[204:207], v[2:5]
	v_mfma_f32_16x16x32_bf16 v[54:57], v[164:167], v[180:183], v[54:57]
	v_mfma_f32_16x16x32_bf16 v[50:53], v[172:175], v[180:183], v[50:53]
	v_mfma_f32_16x16x32_bf16 v[38:41], v[164:167], v[192:195], v[38:41]
	v_mfma_f32_16x16x32_bf16 v[34:37], v[172:175], v[192:195], v[34:37]
	v_mfma_f32_16x16x32_bf16 v[22:25], v[164:167], v[200:203], v[22:25]
	v_mfma_f32_16x16x32_bf16 v[18:21], v[172:175], v[200:203], v[18:21]
	v_mfma_f32_16x16x32_bf16 v[6:9], v[164:167], v[208:211], v[6:9]
	v_mfma_f32_16x16x32_bf16 v[2:5], v[172:175], v[208:211], v[2:5]
	s_setprio 0
	s_barrier
	s_cmp_ge_i32 s58, s55
	s_mov_b64 s[46:47], s[48:49]
	s_mov_b32 s50, s58
	s_cbranch_scc0 .LBB0_131

; #define PG8_STAGE(bufoff, gbase, voff) do { _Pragma("unroll") for (int _i = 0; _i < 2; ++_i) \
;         __builtin_amdgcn_global_load_lds((const unsigned*)((const char*)(gbase) + (voff)[_i]), (LAS unsigned*)(lds + (bufoff) + ldsw + _i * 8192), 16, 0, 0); } while (0)
; #define PG8_LDA(dst, b, h) do { _Pragma("unroll") for (int m = 0; m < 4; ++m) _Pragma("unroll") for (int k = 0; k < 2; ++k) dst[m][k] = *(const LAS bf16x8*)(lds + PG8_SA(b, h) + aoff + m * 2048 + k * 1024); } while (0)
; #define PG8_LDB(dst, b, h) do { _Pragma("unroll") for (int n = 0; n < 2; ++n) _Pragma("unroll") for (int k = 0; k < 2; ++k) dst[n][k] = *(const LAS bf16x8*)(lds + PG8_SB(b, h) + boff + n * 2048 + k * 1024); } while (0)
; #define PG8_MMA(ai, bj, At, Bt) do { __builtin_amdgcn_s_setprio(1); _Pragma("unroll") for (int m = 0; m < 4; ++m) _Pragma("unroll") for (int n = 0; n < 2; ++n) _Pragma("unroll") for (int k = 0; k < 2; ++k) \
;         acc[ai][bj][m][n] = __builtin_amdgcn_mfma_f32_16x16x32_bf16(Bt[n][k], At[m][k], acc[ai][bj][m][n], 0, 0, 0); __builtin_amdgcn_s_setprio(0); } while (0)
; #define PG8_WAIT_V(n) asm volatile("s_waitcnt vmcnt(" #n ")" ::: "memory")
; #define PG8_WAIT_L(n) asm volatile("s_waitcnt lgkmcnt(" #n ")" ::: "memory")
; #define PG8_BAR __builtin_amdgcn_s_barrier()
; template <class Epi, class Sched>
; __device__ __forceinline__ void gemm_phase(LAS unsigned char* lds, const Gemm g, const Sched& S, const Epi& E) {
;     ...
;         for (int t = 0; t < nt; t += 2) {
;             const bool last = (t == nt - 2);
;             const char* a1 = cA + (size_t)(t + 1) * kstep;
;             const char* a2 = last ? nA : cA + (size_t)(t + 2) * kstep; const char* b2 = last ? nB : cB + (size_t)(t + 2) * kstep;
;             const char* a3 = a2 + kstep; const char* b3 = b2 + kstep;
;             if (last && has_next) S.a_ready(nxt);
;             PG8_LDB(B0, 0, 0); PG8_LDB(B1, 0, 1); PG8_SCHED; PG8_LDA(At, 0, 0); PG8_STAGE(PG8_SA(1, 1), a1 + hstep, voffA);
;             PG8_WAIT_V(8); PG8_WAIT_L(0); PG8_BAR; PG8_MMA(0, 0, At, B0); PG8_MMA(0, 1, At, B1); PG8_BAR; PG8_SCHED;
;             PG8_LDA(At, 0, 1); PG8_STAGE(PG8_SB(0, 0), b2, voffB); PG8_STAGE(PG8_SB(0, 1), b2 + hstep, voffB); PG8_STAGE(PG8_SA(0, 0), a2, voffA);
;             PG8_WAIT_V(8); PG8_WAIT_L(0); PG8_BAR; PG8_MMA(1, 0, At, B0); PG8_MMA(1, 1, At, B1); PG8_BAR; PG8_SCHED;
.LBB0_406:
	s_add_i32 s48, s44, 2
	s_add_u32 s42, s40, 0x100
	s_addc_u32 s43, s41, 0
	s_cmp_lg_u32 s47, s44
	s_cselect_b32 s49, s42, 0
	s_cselect_b32 s1, s43, 0
	s_add_u32 s44, s10, s49
	s_addc_u32 s45, s11, s1
	s_add_i32 s52, 0, 0x10000
	s_add_u32 s50, s26, s49
	v_add_u32_e32 v136, s52, v107
	s_addc_u32 s51, s27, s1
	s_add_i32 s1, 0, 0x14000
	ds_read_b128 v[146:149], v136
	ds_read_b128 v[150:153], v136 offset:1024
	ds_read_b128 v[154:157], v136 offset:2048
	ds_read_b128 v[158:161], v136 offset:3072
	v_add_u32_e32 v136, s1, v107
	ds_read_b128 v[162:165], v136
	ds_read_b128 v[166:169], v136 offset:1024
	ds_read_b128 v[170:173], v136 offset:2048
	ds_read_b128 v[174:177], v136 offset:3072
	v_lshl_add_u64 v[136:137], v[130:131], 0, s[40:41]
	s_add_i32 m0, s9, 0xc000
	ds_read_b128 v[178:181], v135
	ds_read_b128 v[182:185], v135 offset:1024
	ds_read_b128 v[192:195], v135 offset:2048
	ds_read_b128 v[196:199], v135 offset:3072
	ds_read_b128 v[200:203], v135 offset:4096
	ds_read_b128 v[204:207], v135 offset:5120
	ds_read_b128 v[208:211], v135 offset:6144
	ds_read_b128 v[212:215], v135 offset:7168
	global_load_lds_dwordx4 v[136:137], off
	v_lshl_add_u64 v[136:137], v[132:133], 0, s[40:41]
	s_add_i32 m0, s9, 0xe000
	s_nop 0
	global_load_lds_dwordx4 v[136:137], off
	s_waitcnt vmcnt(8)
	s_waitcnt lgkmcnt(0)
	s_barrier
	s_setprio 3
	s_waitcnt lgkmcnt(0)
	v_mfma_f32_16x16x32_bf16 v[142:145], v[146:149], v[178:181], v[142:145]
	v_mfma_f32_16x16x32_bf16 v[136:139], v[154:157], v[178:181], v[138:141]
	v_mfma_f32_16x16x32_bf16 v[114:117], v[146:149], v[192:195], v[114:117]
	v_mfma_f32_16x16x32_bf16 v[110:113], v[154:157], v[192:195], v[110:113]
	v_mfma_f32_16x16x32_bf16 v[94:97], v[146:149], v[200:203], v[94:97]
	v_mfma_f32_16x16x32_bf16 v[90:93], v[154:157], v[200:203], v[90:93]
	v_mfma_f32_16x16x32_bf16 v[78:81], v[146:149], v[208:211], v[78:81]
	v_mfma_f32_16x16x32_bf16 v[74:77], v[154:157], v[208:211], v[74:77]
	v_mfma_f32_16x16x32_bf16 v[142:145], v[150:153], v[182:185], v[142:145]
	v_mfma_f32_16x16x32_bf16 v[136:139], v[158:161], v[182:185], v[136:139]
	v_mfma_f32_16x16x32_bf16 v[114:117], v[150:153], v[196:199], v[114:117]
	v_mfma_f32_16x16x32_bf16 v[110:113], v[158:161], v[196:199], v[110:113]
	v_mfma_f32_16x16x32_bf16 v[94:97], v[150:153], v[204:207], v[94:97]
	v_mfma_f32_16x16x32_bf16 v[90:93], v[158:161], v[204:207], v[90:93]
	v_mfma_f32_16x16x32_bf16 v[78:81], v[150:153], v[212:215], v[78:81]
	v_mfma_f32_16x16x32_bf16 v[74:77], v[158:161], v[212:215], v[74:77]
	s_setprio 0
	s_setprio 3
	v_mfma_f32_16x16x32_bf16 v[126:129], v[162:165], v[178:181], v[126:129]
	v_mfma_f32_16x16x32_bf16 v[122:125], v[170:173], v[178:181], v[122:125]
	v_mfma_f32_16x16x32_bf16 v[102:105], v[162:165], v[192:195], v[102:105]
	v_mfma_f32_16x16x32_bf16 v[98:101], v[170:173], v[192:195], v[98:101]
	v_mfma_f32_16x16x32_bf16 v[86:89], v[162:165], v[200:203], v[86:89]
	v_mfma_f32_16x16x32_bf16 v[82:85], v[170:173], v[200:203], v[82:85]
	v_mfma_f32_16x16x32_bf16 v[70:73], v[162:165], v[208:211], v[70:73]
	v_mfma_f32_16x16x32_bf16 v[66:69], v[170:173], v[208:211], v[66:69]
	v_mfma_f32_16x16x32_bf16 v[126:129], v[166:169], v[182:185], v[126:129]
	v_mfma_f32_16x16x32_bf16 v[122:125], v[174:177], v[182:185], v[122:125]
	v_mfma_f32_16x16x32_bf16 v[102:105], v[166:169], v[196:199], v[102:105]
	v_mfma_f32_16x16x32_bf16 v[98:101], v[174:177], v[196:199], v[98:101]
	v_mfma_f32_16x16x32_bf16 v[86:89], v[166:169], v[204:207], v[86:89]
	v_mfma_f32_16x16x32_bf16 v[82:85], v[174:177], v[204:207], v[82:85]
	v_mfma_f32_16x16x32_bf16 v[70:73], v[166:169], v[212:215], v[70:73]
	v_mfma_f32_16x16x32_bf16 v[66:69], v[174:177], v[212:215], v[66:69]
	s_setprio 0
	s_barrier
	s_add_i32 s40, s52, s8
	v_lshl_add_u64 v[186:187], s[50:51], 0, v[0:1]
	s_mov_b32 m0, s40
	ds_read_b128 v[178:181], v135 offset:16384
	ds_read_b128 v[182:185], v135 offset:17408
	ds_read_b128 v[192:195], v135 offset:18432
	ds_read_b128 v[196:199], v135 offset:19456
	ds_read_b128 v[200:203], v135 offset:20480
	ds_read_b128 v[204:207], v135 offset:21504
	ds_read_b128 v[208:211], v135 offset:22528
	ds_read_b128 v[212:215], v135 offset:23552
	global_load_lds_dwordx4 v[186:187], off
	s_add_i32 m0, s40, 0x2000
	s_add_u32 s40, s50, s38
	v_lshl_add_u64 v[216:217], s[50:51], 0, v[108:109]
	s_addc_u32 s41, s51, s39
	s_add_i32 s1, s1, s8
	global_load_lds_dwordx4 v[216:217], off
	v_lshl_add_u64 v[238:239], s[40:41], 0, v[0:1]
	s_mov_b32 m0, s1
	v_lshl_add_u64 v[240:241], s[40:41], 0, v[108:109]
	global_load_lds_dwordx4 v[238:239], off
	s_add_i32 m0, s1, 0x2000
	v_lshl_add_u64 v[244:245], s[44:45], 0, v[120:121]
	global_load_lds_dwordx4 v[240:241], off
	s_mov_b32 m0, s9
	v_lshl_add_u64 v[246:247], s[44:45], 0, v[118:119]
	global_load_lds_dwordx4 v[244:245], off
	s_mov_b32 m0, s18
	s_nop 0
	global_load_lds_dwordx4 v[246:247], off
	s_waitcnt vmcnt(8)
	s_waitcnt lgkmcnt(0)
	s_barrier
; #define PG8_STAGE(bufoff, gbase, voff) do { _Pragma("unroll") for (int _i = 0; _i < 2; ++_i) \
;         __builtin_amdgcn_global_load_lds((const unsigned*)((const char*)(gbase) + (voff)[_i]), (LAS unsigned*)(lds + (bufoff) + ldsw + _i * 8192), 16, 0, 0); } while (0)
; #define PG8_LDA(dst, b, h) do { _Pragma("unroll") for (int m = 0; m < 4; ++m) _Pragma("unroll") for (int k = 0; k < 2; ++k) dst[m][k] = *(const LAS bf16x8*)(lds + PG8_SA(b, h) + aoff + m * 2048 + k * 1024); } while (0)
; #define PG8_LDB(dst, b, h) do { _Pragma("unroll") for (int n = 0; n < 2; ++n) _Pragma("unroll") for (int k = 0; k < 2; ++k) dst[n][k] = *(const LAS bf16x8*)(lds + PG8_SB(b, h) + boff + n * 2048 + k * 1024); } while (0)
; #define PG8_MMA(ai, bj, At, Bt) do { __builtin_amdgcn_s_setprio(1); _Pragma("unroll") for (int m = 0; m < 4; ++m) _Pragma("unroll") for (int n = 0; n < 2; ++n) _Pragma("unroll") for (int k = 0; k < 2; ++k) \
;         acc[ai][bj][m][n] = __builtin_amdgcn_mfma_f32_16x16x32_bf16(Bt[n][k], At[m][k], acc[ai][bj][m][n], 0, 0, 0); __builtin_amdgcn_s_setprio(0); } while (0)
; #define PG8_WAIT_V(n) asm volatile("s_waitcnt vmcnt(" #n ")" ::: "memory")
; #define PG8_WAIT_L(n) asm volatile("s_waitcnt lgkmcnt(" #n ")" ::: "memory")
; #define PG8_BAR __builtin_amdgcn_s_barrier()
; #define PG8_SCHED __builtin_amdgcn_sched_barrier(0)
; template <class Epi, class Sched>
; __device__ __forceinline__ void gemm_phase(LAS unsigned char* lds, const Gemm g, const Sched& S, const Epi& E) {
;     ...
;             PG8_WAIT_V(8); PG8_WAIT_L(0); PG8_BAR; PG8_MMA(1, 0, At, B0); PG8_MMA(1, 1, At, B1); PG8_BAR; PG8_SCHED;
;             PG8_LDB(B0, 1, 0); PG8_LDB(B1, 1, 1); PG8_SCHED; PG8_LDA(At, 1, 0); PG8_STAGE(PG8_SA(0, 1), a2 + hstep, voffA);
;             PG8_WAIT_V(8); PG8_WAIT_L(0); PG8_BAR; PG8_MMA(0, 0, At, B0); PG8_MMA(0, 1, At, B1); PG8_BAR; PG8_SCHED;
	s_setprio 3
	s_waitcnt lgkmcnt(0)
	v_mfma_f32_16x16x32_bf16 v[62:65], v[146:149], v[178:181], v[62:65]
	v_mfma_f32_16x16x32_bf16 v[58:61], v[154:157], v[178:181], v[58:61]
	v_mfma_f32_16x16x32_bf16 v[46:49], v[146:149], v[192:195], v[46:49]
	v_mfma_f32_16x16x32_bf16 v[42:45], v[154:157], v[192:195], v[42:45]
	v_mfma_f32_16x16x32_bf16 v[30:33], v[146:149], v[200:203], v[30:33]
	v_mfma_f32_16x16x32_bf16 v[26:29], v[154:157], v[200:203], v[26:29]
	v_mfma_f32_16x16x32_bf16 v[14:17], v[146:149], v[208:211], v[14:17]
	v_mfma_f32_16x16x32_bf16 v[10:13], v[154:157], v[208:211], v[10:13]
	v_mfma_f32_16x16x32_bf16 v[62:65], v[150:153], v[182:185], v[62:65]
	v_mfma_f32_16x16x32_bf16 v[58:61], v[158:161], v[182:185], v[58:61]
	v_mfma_f32_16x16x32_bf16 v[46:49], v[150:153], v[196:199], v[46:49]
	v_mfma_f32_16x16x32_bf16 v[42:45], v[158:161], v[196:199], v[42:45]
	v_mfma_f32_16x16x32_bf16 v[30:33], v[150:153], v[204:207], v[30:33]
	v_mfma_f32_16x16x32_bf16 v[26:29], v[158:161], v[204:207], v[26:29]
	v_mfma_f32_16x16x32_bf16 v[14:17], v[150:153], v[212:215], v[14:17]
	v_mfma_f32_16x16x32_bf16 v[10:13], v[158:161], v[212:215], v[10:13]
	s_setprio 0
	s_setprio 3
	v_mfma_f32_16x16x32_bf16 v[54:57], v[162:165], v[178:181], v[54:57]
	v_mfma_f32_16x16x32_bf16 v[50:53], v[170:173], v[178:181], v[50:53]
	v_mfma_f32_16x16x32_bf16 v[38:41], v[162:165], v[192:195], v[38:41]
	v_mfma_f32_16x16x32_bf16 v[34:37], v[170:173], v[192:195], v[34:37]
	v_mfma_f32_16x16x32_bf16 v[22:25], v[162:165], v[200:203], v[22:25]
	v_mfma_f32_16x16x32_bf16 v[18:21], v[170:173], v[200:203], v[18:21]
	v_mfma_f32_16x16x32_bf16 v[6:9], v[162:165], v[208:211], v[6:9]
	v_mfma_f32_16x16x32_bf16 v[2:5], v[170:173], v[208:211], v[2:5]
	v_mfma_f32_16x16x32_bf16 v[54:57], v[166:169], v[182:185], v[54:57]
	v_mfma_f32_16x16x32_bf16 v[50:53], v[174:177], v[182:185], v[50:53]
	v_mfma_f32_16x16x32_bf16 v[38:41], v[166:169], v[196:199], v[38:41]
	v_mfma_f32_16x16x32_bf16 v[34:37], v[174:177], v[196:199], v[34:37]
	v_mfma_f32_16x16x32_bf16 v[22:25], v[166:169], v[204:207], v[22:25]
	v_mfma_f32_16x16x32_bf16 v[18:21], v[174:177], v[204:207], v[18:21]
	v_mfma_f32_16x16x32_bf16 v[6:9], v[166:169], v[212:215], v[6:9]
	v_mfma_f32_16x16x32_bf16 v[2:5], v[174:177], v[212:215], v[2:5]
	s_setprio 0
	s_barrier
	s_add_i32 s1, 0, 0x18000
	v_add_u32_e32 v140, s1, v107
	s_add_i32 s49, 0, 0x1c000
	ds_read_b128 v[146:149], v140
	ds_read_b128 v[150:153], v140 offset:1024
	ds_read_b128 v[154:157], v140 offset:2048
	ds_read_b128 v[158:161], v140 offset:3072
	v_add_u32_e32 v140, s49, v107
	ds_read_b128 v[162:165], v140
	ds_read_b128 v[166:169], v140 offset:1024
	ds_read_b128 v[170:173], v140 offset:2048
	ds_read_b128 v[174:177], v140 offset:3072
	s_add_u32 s40, s44, s38
	s_addc_u32 s41, s45, s39
	s_mov_b32 m0, s19
	v_lshl_add_u64 v[140:141], s[40:41], 0, v[120:121]
	ds_read_b128 v[178:181], v135 offset:32768
	ds_read_b128 v[182:185], v135 offset:33792
	ds_read_b128 v[192:195], v135 offset:34816
	ds_read_b128 v[196:199], v135 offset:35840
	ds_read_b128 v[200:203], v135 offset:36864
	ds_read_b128 v[204:207], v135 offset:37888
	ds_read_b128 v[208:211], v135 offset:38912
	ds_read_b128 v[212:215], v135 offset:39936
	global_load_lds_dwordx4 v[140:141], off
	v_lshl_add_u64 v[140:141], s[40:41], 0, v[118:119]
	s_mov_b32 m0, s20
	s_nop 0
	global_load_lds_dwordx4 v[140:141], off
	s_waitcnt vmcnt(8)
	s_waitcnt lgkmcnt(0)
	s_barrier
	s_setprio 3
	s_waitcnt lgkmcnt(0)
	v_mfma_f32_16x16x32_bf16 v[140:143], v[146:149], v[178:181], v[142:145]
	v_mfma_f32_16x16x32_bf16 v[136:139], v[154:157], v[178:181], v[136:139]
	v_mfma_f32_16x16x32_bf16 v[114:117], v[146:149], v[192:195], v[114:117]
	v_mfma_f32_16x16x32_bf16 v[110:113], v[154:157], v[192:195], v[110:113]
	v_mfma_f32_16x16x32_bf16 v[94:97], v[146:149], v[200:203], v[94:97]
	v_mfma_f32_16x16x32_bf16 v[90:93], v[154:157], v[200:203], v[90:93]
	v_mfma_f32_16x16x32_bf16 v[78:81], v[146:149], v[208:211], v[78:81]
	v_mfma_f32_16x16x32_bf16 v[74:77], v[154:157], v[208:211], v[74:77]
	v_mfma_f32_16x16x32_bf16 v[142:145], v[150:153], v[182:185], v[140:143]
	v_mfma_f32_16x16x32_bf16 v[138:141], v[158:161], v[182:185], v[136:139]
	v_mfma_f32_16x16x32_bf16 v[114:117], v[150:153], v[196:199], v[114:117]
	v_mfma_f32_16x16x32_bf16 v[110:113], v[158:161], v[196:199], v[110:113]
	v_mfma_f32_16x16x32_bf16 v[94:97], v[150:153], v[204:207], v[94:97]
	v_mfma_f32_16x16x32_bf16 v[90:93], v[158:161], v[204:207], v[90:93]
	v_mfma_f32_16x16x32_bf16 v[78:81], v[150:153], v[212:215], v[78:81]
	v_mfma_f32_16x16x32_bf16 v[74:77], v[158:161], v[212:215], v[74:77]
	s_setprio 0
	s_setprio 3
	v_mfma_f32_16x16x32_bf16 v[126:129], v[162:165], v[178:181], v[126:129]
	v_mfma_f32_16x16x32_bf16 v[122:125], v[170:173], v[178:181], v[122:125]
	v_mfma_f32_16x16x32_bf16 v[102:105], v[162:165], v[192:195], v[102:105]
	v_mfma_f32_16x16x32_bf16 v[98:101], v[170:173], v[192:195], v[98:101]
	v_mfma_f32_16x16x32_bf16 v[86:89], v[162:165], v[200:203], v[86:89]
	v_mfma_f32_16x16x32_bf16 v[82:85], v[170:173], v[200:203], v[82:85]
	v_mfma_f32_16x16x32_bf16 v[70:73], v[162:165], v[208:211], v[70:73]
	v_mfma_f32_16x16x32_bf16 v[66:69], v[170:173], v[208:211], v[66:69]
	v_mfma_f32_16x16x32_bf16 v[126:129], v[166:169], v[182:185], v[126:129]
	v_mfma_f32_16x16x32_bf16 v[122:125], v[174:177], v[182:185], v[122:125]
	v_mfma_f32_16x16x32_bf16 v[102:105], v[166:169], v[196:199], v[102:105]
	v_mfma_f32_16x16x32_bf16 v[98:101], v[174:177], v[196:199], v[98:101]
	v_mfma_f32_16x16x32_bf16 v[86:89], v[166:169], v[204:207], v[86:89]
	v_mfma_f32_16x16x32_bf16 v[82:85], v[174:177], v[204:207], v[82:85]
	v_mfma_f32_16x16x32_bf16 v[70:73], v[166:169], v[212:215], v[70:73]
	v_mfma_f32_16x16x32_bf16 v[66:69], v[174:177], v[212:215], v[66:69]
	s_setprio 0
	s_barrier
; #define PG8_STAGE(bufoff, gbase, voff) do { _Pragma("unroll") for (int _i = 0; _i < 2; ++_i) \
;         __builtin_amdgcn_global_load_lds((const unsigned*)((const char*)(gbase) + (voff)[_i]), (LAS unsigned*)(lds + (bufoff) + ldsw + _i * 8192), 16, 0, 0); } while (0)
; #define PG8_LDA(dst, b, h) do { _Pragma("unroll") for (int m = 0; m < 4; ++m) _Pragma("unroll") for (int k = 0; k < 2; ++k) dst[m][k] = *(const LAS bf16x8*)(lds + PG8_SA(b, h) + aoff + m * 2048 + k * 1024); } while (0)
; #define PG8_MMA(ai, bj, At, Bt) do { __builtin_amdgcn_s_setprio(1); _Pragma("unroll") for (int m = 0; m < 4; ++m) _Pragma("unroll") for (int n = 0; n < 2; ++n) _Pragma("unroll") for (int k = 0; k < 2; ++k) \
;         acc[ai][bj][m][n] = __builtin_amdgcn_mfma_f32_16x16x32_bf16(Bt[n][k], At[m][k], acc[ai][bj][m][n], 0, 0, 0); __builtin_amdgcn_s_setprio(0); } while (0)
; #define PG8_WAIT_V(n) asm volatile("s_waitcnt vmcnt(" #n ")" ::: "memory")
; #define PG8_WAIT_L(n) asm volatile("s_waitcnt lgkmcnt(" #n ")" ::: "memory")
; #define PG8_BAR __builtin_amdgcn_s_barrier()
; #define PG8_SCHED __builtin_amdgcn_sched_barrier(0)
; template <class Epi, class Sched>
; __device__ __forceinline__ void gemm_phase(LAS unsigned char* lds, const Gemm g, const Sched& S, const Epi& E) {
;     ...
;             PG8_LDA(At, 1, 1); PG8_STAGE(PG8_SB(1, 0), b3, voffB); PG8_STAGE(PG8_SB(1, 1), b3 + hstep, voffB); PG8_STAGE(PG8_SA(1, 0), a3, voffA);
;             PG8_WAIT_V(8); PG8_WAIT_L(0); PG8_BAR; PG8_MMA(1, 0, At, B0); PG8_MMA(1, 1, At, B1); PG8_BAR; PG8_SCHED;
;         }
	s_add_i32 s1, s1, s8
	v_lshl_add_u64 v[136:137], v[186:187], 0, s[6:7]
	s_mov_b32 m0, s1
	ds_read_b128 v[178:181], v135 offset:49152
	ds_read_b128 v[182:185], v135 offset:50176
	ds_read_b128 v[192:195], v135 offset:51200
	ds_read_b128 v[196:199], v135 offset:52224
	ds_read_b128 v[200:203], v135 offset:53248
	ds_read_b128 v[204:207], v135 offset:54272
	ds_read_b128 v[208:211], v135 offset:55296
	ds_read_b128 v[212:215], v135 offset:56320
	global_load_lds_dwordx4 v[136:137], off
	v_lshl_add_u64 v[136:137], v[216:217], 0, s[6:7]
	s_add_i32 m0, s1, 0x2000
	s_add_i32 s1, s49, s8
	global_load_lds_dwordx4 v[136:137], off
	v_lshl_add_u64 v[136:137], v[238:239], 0, s[6:7]
	s_mov_b32 m0, s1
	s_nop 0
	global_load_lds_dwordx4 v[136:137], off
	v_lshl_add_u64 v[136:137], v[240:241], 0, s[6:7]
	s_add_i32 m0, s1, 0x2000
	s_nop 0
	global_load_lds_dwordx4 v[136:137], off
	v_lshl_add_u64 v[136:137], v[244:245], 0, s[6:7]
	s_mov_b32 m0, s21
	s_nop 0
	global_load_lds_dwordx4 v[136:137], off
	v_lshl_add_u64 v[136:137], v[246:247], 0, s[6:7]
	s_mov_b32 m0, s36
	s_nop 0
	global_load_lds_dwordx4 v[136:137], off
	s_waitcnt vmcnt(8)
	s_waitcnt lgkmcnt(0)
	s_barrier
	s_setprio 3
	s_waitcnt lgkmcnt(0)
	v_mfma_f32_16x16x32_bf16 v[62:65], v[146:149], v[178:181], v[62:65]
	v_mfma_f32_16x16x32_bf16 v[58:61], v[154:157], v[178:181], v[58:61]
	v_mfma_f32_16x16x32_bf16 v[46:49], v[146:149], v[192:195], v[46:49]
	v_mfma_f32_16x16x32_bf16 v[42:45], v[154:157], v[192:195], v[42:45]
	v_mfma_f32_16x16x32_bf16 v[30:33], v[146:149], v[200:203], v[30:33]
	v_mfma_f32_16x16x32_bf16 v[26:29], v[154:157], v[200:203], v[26:29]
	v_mfma_f32_16x16x32_bf16 v[14:17], v[146:149], v[208:211], v[14:17]
	v_mfma_f32_16x16x32_bf16 v[10:13], v[154:157], v[208:211], v[10:13]
	v_mfma_f32_16x16x32_bf16 v[62:65], v[150:153], v[182:185], v[62:65]
	v_mfma_f32_16x16x32_bf16 v[58:61], v[158:161], v[182:185], v[58:61]
	v_mfma_f32_16x16x32_bf16 v[46:49], v[150:153], v[196:199], v[46:49]
	v_mfma_f32_16x16x32_bf16 v[42:45], v[158:161], v[196:199], v[42:45]
	v_mfma_f32_16x16x32_bf16 v[30:33], v[150:153], v[204:207], v[30:33]
	v_mfma_f32_16x16x32_bf16 v[26:29], v[158:161], v[204:207], v[26:29]
	v_mfma_f32_16x16x32_bf16 v[14:17], v[150:153], v[212:215], v[14:17]
	v_mfma_f32_16x16x32_bf16 v[10:13], v[158:161], v[212:215], v[10:13]
	s_setprio 0
	s_setprio 3
	v_mfma_f32_16x16x32_bf16 v[54:57], v[162:165], v[178:181], v[54:57]
	v_mfma_f32_16x16x32_bf16 v[50:53], v[170:173], v[178:181], v[50:53]
	v_mfma_f32_16x16x32_bf16 v[38:41], v[162:165], v[192:195], v[38:41]
	v_mfma_f32_16x16x32_bf16 v[34:37], v[170:173], v[192:195], v[34:37]
	v_mfma_f32_16x16x32_bf16 v[22:25], v[162:165], v[200:203], v[22:25]
	v_mfma_f32_16x16x32_bf16 v[18:21], v[170:173], v[200:203], v[18:21]
	v_mfma_f32_16x16x32_bf16 v[6:9], v[162:165], v[208:211], v[6:9]
	v_mfma_f32_16x16x32_bf16 v[2:5], v[170:173], v[208:211], v[2:5]
	v_mfma_f32_16x16x32_bf16 v[54:57], v[166:169], v[182:185], v[54:57]
	v_mfma_f32_16x16x32_bf16 v[50:53], v[174:177], v[182:185], v[50:53]
	v_mfma_f32_16x16x32_bf16 v[38:41], v[166:169], v[196:199], v[38:41]
	v_mfma_f32_16x16x32_bf16 v[34:37], v[174:177], v[196:199], v[34:37]
	v_mfma_f32_16x16x32_bf16 v[22:25], v[166:169], v[204:207], v[22:25]
	v_mfma_f32_16x16x32_bf16 v[18:21], v[174:177], v[204:207], v[18:21]
	v_mfma_f32_16x16x32_bf16 v[6:9], v[166:169], v[212:215], v[6:9]
	v_mfma_f32_16x16x32_bf16 v[2:5], v[174:177], v[212:215], v[2:5]
	s_setprio 0
	s_barrier
	s_cmp_ge_i32 s48, s46
	s_mov_b64 s[40:41], s[42:43]
	s_mov_b32 s44, s48
	s_cbranch_scc0 .LBB0_406

; #define PG8_STAGE(bufoff, gbase, voff) do { _Pragma("unroll") for (int _i = 0; _i < 2; ++_i) \
;         __builtin_amdgcn_global_load_lds((const unsigned*)((const char*)(gbase) + (voff)[_i]), (LAS unsigned*)(lds + (bufoff) + ldsw + _i * 8192), 16, 0, 0); } while (0)
; #define PG8_LDA(dst, b, h) do { _Pragma("unroll") for (int m = 0; m < 4; ++m) _Pragma("unroll") for (int k = 0; k < 2; ++k) dst[m][k] = *(const LAS bf16x8*)(lds + PG8_SA(b, h) + aoff + m * 2048 + k * 1024); } while (0)
; #define PG8_LDB(dst, b, h) do { _Pragma("unroll") for (int n = 0; n < 2; ++n) _Pragma("unroll") for (int k = 0; k < 2; ++k) dst[n][k] = *(const LAS bf16x8*)(lds + PG8_SB(b, h) + boff + n * 2048 + k * 1024); } while (0)
; #define PG8_MMA(ai, bj, At, Bt) do { __builtin_amdgcn_s_setprio(1); _Pragma("unroll") for (int m = 0; m < 4; ++m) _Pragma("unroll") for (int n = 0; n < 2; ++n) _Pragma("unroll") for (int k = 0; k < 2; ++k) \
;         acc[ai][bj][m][n] = __builtin_amdgcn_mfma_f32_16x16x32_bf16(Bt[n][k], At[m][k], acc[ai][bj][m][n], 0, 0, 0); __builtin_amdgcn_s_setprio(0); } while (0)
; #define PG8_WAIT_V(n) asm volatile("s_waitcnt vmcnt(" #n ")" ::: "memory")
; #define PG8_WAIT_L(n) asm volatile("s_waitcnt lgkmcnt(" #n ")" ::: "memory")
; #define PG8_BAR __builtin_amdgcn_s_barrier()
; template <class Epi, class Sched>
; __device__ __forceinline__ void gemm_phase(LAS unsigned char* lds, const Gemm g, const Sched& S, const Epi& E) {
;     ...
;         for (int t = 0; t < nt; t += 2) {
;             const bool last = (t == nt - 2);
;             const char* a1 = cA + (size_t)(t + 1) * kstep;
;             const char* a2 = last ? nA : cA + (size_t)(t + 2) * kstep; const char* b2 = last ? nB : cB + (size_t)(t + 2) * kstep;
;             const char* a3 = a2 + kstep; const char* b3 = b2 + kstep;
;             if (last && has_next) S.a_ready(nxt);
;             PG8_LDB(B0, 0, 0); PG8_LDB(B1, 0, 1); PG8_SCHED; PG8_LDA(At, 0, 0); PG8_STAGE(PG8_SA(1, 1), a1 + hstep, voffA);
;             PG8_WAIT_V(8); PG8_WAIT_L(0); PG8_BAR; PG8_MMA(0, 0, At, B0); PG8_MMA(0, 1, At, B1); PG8_BAR; PG8_SCHED;
;             PG8_LDA(At, 0, 1); PG8_STAGE(PG8_SB(0, 0), b2, voffB); PG8_STAGE(PG8_SB(0, 1), b2 + hstep, voffB); PG8_STAGE(PG8_SA(0, 0), a2, voffA);
;             PG8_WAIT_V(8); PG8_WAIT_L(0); PG8_BAR; PG8_MMA(1, 0, At, B0); PG8_MMA(1, 1, At, B1); PG8_BAR; PG8_SCHED;
.LBB0_418:
	s_add_i32 s58, s52, 2
	s_add_u32 s50, s48, 0x100
	s_addc_u32 s51, s49, 0
	s_add_u32 s1, s9, s48
	s_addc_u32 s53, s36, s49
	s_cmp_eq_u32 s56, s52
	s_cselect_b32 s52, 0, s50
	s_cselect_b32 s59, 0, s51
	s_cselect_b32 s60, s46, s1
	s_cselect_b32 s61, s47, s53
	s_add_u32 s52, s2, s52
	s_addc_u32 s53, s3, s59
	s_add_i32 s1, 0, 0x10000
	s_add_i32 s59, 0, 0x14000
	v_add_u32_e32 v154, s1, v160
	v_add_u32_e32 v158, s59, v160
	ds_read_b128 v[130:133], v154
	ds_read_b128 v[134:137], v154 offset:1024
	ds_read_b128 v[138:141], v154 offset:2048
	ds_read_b128 v[154:157], v154 offset:3072
	ds_read_b128 v[162:165], v158
	ds_read_b128 v[166:169], v158 offset:1024
	ds_read_b128 v[170:173], v158 offset:2048
	ds_read_b128 v[174:177], v158 offset:3072
	s_add_u32 s48, s48, s2
	s_addc_u32 s49, s49, s3
	s_add_u32 s48, s48, s26
	s_addc_u32 s49, s49, s27
	s_add_u32 s48, s48, 0x80
	s_addc_u32 s49, s49, 0
	s_add_i32 m0, s5, 0xc000
	ds_read_b128 v[178:181], v161
	ds_read_b128 v[182:185], v161 offset:1024
	ds_read_b128 v[192:195], v161 offset:2048
	ds_read_b128 v[196:199], v161 offset:3072
	ds_read_b128 v[200:203], v161 offset:4096
	ds_read_b128 v[204:207], v161 offset:5120
	ds_read_b128 v[208:211], v161 offset:6144
	ds_read_b128 v[212:215], v161 offset:7168
	global_load_lds_dwordx4 v146, s[48:49]
	s_add_i32 m0, s5, 0xe000
	s_nop 0
	global_load_lds_dwordx4 v144, s[48:49]
	s_waitcnt vmcnt(8)
	s_waitcnt lgkmcnt(0)
	s_barrier
	s_setprio 3
	s_waitcnt lgkmcnt(0)
	v_mfma_f32_16x16x32_bf16 v[122:125], v[130:133], v[178:181], v[122:125]
	v_mfma_f32_16x16x32_bf16 v[126:129], v[138:141], v[178:181], v[126:129]
	v_mfma_f32_16x16x32_bf16 v[110:113], v[130:133], v[192:195], v[110:113]
	v_mfma_f32_16x16x32_bf16 v[106:109], v[138:141], v[192:195], v[106:109]
	v_mfma_f32_16x16x32_bf16 v[94:97], v[130:133], v[200:203], v[94:97]
	v_mfma_f32_16x16x32_bf16 v[90:93], v[138:141], v[200:203], v[90:93]
	v_mfma_f32_16x16x32_bf16 v[78:81], v[130:133], v[208:211], v[78:81]
	v_mfma_f32_16x16x32_bf16 v[74:77], v[138:141], v[208:211], v[74:77]
	v_mfma_f32_16x16x32_bf16 v[122:125], v[134:137], v[182:185], v[122:125]
	v_mfma_f32_16x16x32_bf16 v[126:129], v[154:157], v[182:185], v[126:129]
	v_mfma_f32_16x16x32_bf16 v[110:113], v[134:137], v[196:199], v[110:113]
	v_mfma_f32_16x16x32_bf16 v[106:109], v[154:157], v[196:199], v[106:109]
	v_mfma_f32_16x16x32_bf16 v[94:97], v[134:137], v[204:207], v[94:97]
	v_mfma_f32_16x16x32_bf16 v[90:93], v[154:157], v[204:207], v[90:93]
	v_mfma_f32_16x16x32_bf16 v[78:81], v[134:137], v[212:215], v[78:81]
	v_mfma_f32_16x16x32_bf16 v[74:77], v[154:157], v[212:215], v[74:77]
	s_setprio 0
	s_setprio 3
	v_mfma_f32_16x16x32_bf16 v[118:121], v[162:165], v[178:181], v[118:121]
	v_mfma_f32_16x16x32_bf16 v[114:117], v[170:173], v[178:181], v[114:117]
	v_mfma_f32_16x16x32_bf16 v[102:105], v[162:165], v[192:195], v[102:105]
	v_mfma_f32_16x16x32_bf16 v[98:101], v[170:173], v[192:195], v[98:101]
	v_mfma_f32_16x16x32_bf16 v[86:89], v[162:165], v[200:203], v[86:89]
	v_mfma_f32_16x16x32_bf16 v[82:85], v[170:173], v[200:203], v[82:85]
	v_mfma_f32_16x16x32_bf16 v[70:73], v[162:165], v[208:211], v[70:73]
	v_mfma_f32_16x16x32_bf16 v[66:69], v[170:173], v[208:211], v[66:69]
	v_mfma_f32_16x16x32_bf16 v[118:121], v[166:169], v[182:185], v[118:121]
	v_mfma_f32_16x16x32_bf16 v[114:117], v[174:177], v[182:185], v[114:117]
	v_mfma_f32_16x16x32_bf16 v[102:105], v[166:169], v[196:199], v[102:105]
	v_mfma_f32_16x16x32_bf16 v[98:101], v[174:177], v[196:199], v[98:101]
	v_mfma_f32_16x16x32_bf16 v[86:89], v[166:169], v[204:207], v[86:89]
	v_mfma_f32_16x16x32_bf16 v[82:85], v[174:177], v[204:207], v[82:85]
	v_mfma_f32_16x16x32_bf16 v[70:73], v[166:169], v[212:215], v[70:73]
	v_mfma_f32_16x16x32_bf16 v[66:69], v[174:177], v[212:215], v[66:69]
	s_setprio 0
	s_barrier
	s_add_i32 s1, s1, s4
	s_mov_b32 m0, s1
	ds_read_b128 v[178:181], v161 offset:16384
	ds_read_b128 v[182:185], v161 offset:17408
	ds_read_b128 v[192:195], v161 offset:18432
	ds_read_b128 v[196:199], v161 offset:19456
	ds_read_b128 v[200:203], v161 offset:20480
	ds_read_b128 v[204:207], v161 offset:21504
	ds_read_b128 v[208:211], v161 offset:22528
	ds_read_b128 v[212:215], v161 offset:23552
	global_load_lds_dwordx4 v0, s[60:61]
	s_add_i32 m0, s1, 0x2000
	s_add_u32 s48, s60, s26
	s_addc_u32 s49, s61, s27
	s_add_i32 s1, s59, s4
	global_load_lds_dwordx4 v142, s[60:61]
	s_mov_b32 m0, s1
	s_nop 0
	global_load_lds_dwordx4 v0, s[48:49]
	s_add_i32 m0, s1, 0x2000
	s_nop 0
	global_load_lds_dwordx4 v142, s[48:49]
	s_mov_b32 m0, s5
	s_nop 0
	global_load_lds_dwordx4 v146, s[52:53]
	s_mov_b32 m0, s18
	s_nop 0
	global_load_lds_dwordx4 v144, s[52:53]
	s_waitcnt vmcnt(8)
	s_waitcnt lgkmcnt(0)
	s_barrier
; #define PG8_STAGE(bufoff, gbase, voff) do { _Pragma("unroll") for (int _i = 0; _i < 2; ++_i) \
;         __builtin_amdgcn_global_load_lds((const unsigned*)((const char*)(gbase) + (voff)[_i]), (LAS unsigned*)(lds + (bufoff) + ldsw + _i * 8192), 16, 0, 0); } while (0)
; #define PG8_LDA(dst, b, h) do { _Pragma("unroll") for (int m = 0; m < 4; ++m) _Pragma("unroll") for (int k = 0; k < 2; ++k) dst[m][k] = *(const LAS bf16x8*)(lds + PG8_SA(b, h) + aoff + m * 2048 + k * 1024); } while (0)
; #define PG8_LDB(dst, b, h) do { _Pragma("unroll") for (int n = 0; n < 2; ++n) _Pragma("unroll") for (int k = 0; k < 2; ++k) dst[n][k] = *(const LAS bf16x8*)(lds + PG8_SB(b, h) + boff + n * 2048 + k * 1024); } while (0)
; #define PG8_MMA(ai, bj, At, Bt) do { __builtin_amdgcn_s_setprio(1); _Pragma("unroll") for (int m = 0; m < 4; ++m) _Pragma("unroll") for (int n = 0; n < 2; ++n) _Pragma("unroll") for (int k = 0; k < 2; ++k) \
;         acc[ai][bj][m][n] = __builtin_amdgcn_mfma_f32_16x16x32_bf16(Bt[n][k], At[m][k], acc[ai][bj][m][n], 0, 0, 0); __builtin_amdgcn_s_setprio(0); } while (0)
; #define PG8_WAIT_V(n) asm volatile("s_waitcnt vmcnt(" #n ")" ::: "memory")
; #define PG8_WAIT_L(n) asm volatile("s_waitcnt lgkmcnt(" #n ")" ::: "memory")
; #define PG8_BAR __builtin_amdgcn_s_barrier()
; #define PG8_SCHED __builtin_amdgcn_sched_barrier(0)
; template <class Epi, class Sched>
; __device__ __forceinline__ void gemm_phase(LAS unsigned char* lds, const Gemm g, const Sched& S, const Epi& E) {
;     ...
;             PG8_WAIT_V(8); PG8_WAIT_L(0); PG8_BAR; PG8_MMA(1, 0, At, B0); PG8_MMA(1, 1, At, B1); PG8_BAR; PG8_SCHED;
;             PG8_LDB(B0, 1, 0); PG8_LDB(B1, 1, 1); PG8_SCHED; PG8_LDA(At, 1, 0); PG8_STAGE(PG8_SA(0, 1), a2 + hstep, voffA);
;             PG8_WAIT_V(8); PG8_WAIT_L(0); PG8_BAR; PG8_MMA(0, 0, At, B0); PG8_MMA(0, 1, At, B1); PG8_BAR; PG8_SCHED;
	s_setprio 3
	s_waitcnt lgkmcnt(0)
	v_mfma_f32_16x16x32_bf16 v[62:65], v[130:133], v[178:181], v[62:65]
	v_mfma_f32_16x16x32_bf16 v[58:61], v[138:141], v[178:181], v[58:61]
	v_mfma_f32_16x16x32_bf16 v[46:49], v[130:133], v[192:195], v[46:49]
	v_mfma_f32_16x16x32_bf16 v[42:45], v[138:141], v[192:195], v[42:45]
	v_mfma_f32_16x16x32_bf16 v[30:33], v[130:133], v[200:203], v[30:33]
	v_mfma_f32_16x16x32_bf16 v[26:29], v[138:141], v[200:203], v[26:29]
	v_mfma_f32_16x16x32_bf16 v[14:17], v[130:133], v[208:211], v[14:17]
	v_mfma_f32_16x16x32_bf16 v[10:13], v[138:141], v[208:211], v[10:13]
	v_mfma_f32_16x16x32_bf16 v[62:65], v[134:137], v[182:185], v[62:65]
	v_mfma_f32_16x16x32_bf16 v[58:61], v[154:157], v[182:185], v[58:61]
	v_mfma_f32_16x16x32_bf16 v[46:49], v[134:137], v[196:199], v[46:49]
	v_mfma_f32_16x16x32_bf16 v[42:45], v[154:157], v[196:199], v[42:45]
	v_mfma_f32_16x16x32_bf16 v[30:33], v[134:137], v[204:207], v[30:33]
	v_mfma_f32_16x16x32_bf16 v[26:29], v[154:157], v[204:207], v[26:29]
	v_mfma_f32_16x16x32_bf16 v[14:17], v[134:137], v[212:215], v[14:17]
	v_mfma_f32_16x16x32_bf16 v[10:13], v[154:157], v[212:215], v[10:13]
	s_setprio 0
	s_setprio 3
	v_mfma_f32_16x16x32_bf16 v[54:57], v[162:165], v[178:181], v[54:57]
	v_mfma_f32_16x16x32_bf16 v[50:53], v[170:173], v[178:181], v[50:53]
	v_mfma_f32_16x16x32_bf16 v[38:41], v[162:165], v[192:195], v[38:41]
	v_mfma_f32_16x16x32_bf16 v[34:37], v[170:173], v[192:195], v[34:37]
	v_mfma_f32_16x16x32_bf16 v[22:25], v[162:165], v[200:203], v[22:25]
	v_mfma_f32_16x16x32_bf16 v[18:21], v[170:173], v[200:203], v[18:21]
	v_mfma_f32_16x16x32_bf16 v[6:9], v[162:165], v[208:211], v[6:9]
	v_mfma_f32_16x16x32_bf16 v[2:5], v[170:173], v[208:211], v[2:5]
	v_mfma_f32_16x16x32_bf16 v[54:57], v[166:169], v[182:185], v[54:57]
	v_mfma_f32_16x16x32_bf16 v[50:53], v[174:177], v[182:185], v[50:53]
	v_mfma_f32_16x16x32_bf16 v[38:41], v[166:169], v[196:199], v[38:41]
	v_mfma_f32_16x16x32_bf16 v[34:37], v[174:177], v[196:199], v[34:37]
	v_mfma_f32_16x16x32_bf16 v[22:25], v[166:169], v[204:207], v[22:25]
	v_mfma_f32_16x16x32_bf16 v[18:21], v[174:177], v[204:207], v[18:21]
	v_mfma_f32_16x16x32_bf16 v[6:9], v[166:169], v[212:215], v[6:9]
	v_mfma_f32_16x16x32_bf16 v[2:5], v[174:177], v[212:215], v[2:5]
	s_setprio 0
	s_barrier
	s_add_i32 s1, 0, 0x18000
	s_add_i32 s59, 0, 0x1c000
	v_add_u32_e32 v154, s1, v160
	v_add_u32_e32 v174, s59, v160
	ds_read_b128 v[130:133], v154
	ds_read_b128 v[134:137], v154 offset:1024
	ds_read_b128 v[138:141], v154 offset:2048
	ds_read_b128 v[154:157], v154 offset:3072
	ds_read_b128 v[162:165], v174
	ds_read_b128 v[166:169], v174 offset:1024
	ds_read_b128 v[170:173], v174 offset:2048
	ds_read_b128 v[174:177], v174 offset:3072
	s_add_u32 s48, s52, s26
	s_addc_u32 s49, s53, s27
	s_mov_b32 m0, s19
	ds_read_b128 v[178:181], v161 offset:32768
	ds_read_b128 v[182:185], v161 offset:33792
	ds_read_b128 v[192:195], v161 offset:34816
	ds_read_b128 v[196:199], v161 offset:35840
	ds_read_b128 v[200:203], v161 offset:36864
	ds_read_b128 v[204:207], v161 offset:37888
	ds_read_b128 v[208:211], v161 offset:38912
	ds_read_b128 v[212:215], v161 offset:39936
	global_load_lds_dwordx4 v146, s[48:49]
	s_mov_b32 m0, s20
	s_nop 0
	global_load_lds_dwordx4 v144, s[48:49]
	s_waitcnt vmcnt(8)
	s_waitcnt lgkmcnt(0)
	s_barrier
	s_setprio 3
	s_waitcnt lgkmcnt(0)
	v_mfma_f32_16x16x32_bf16 v[122:125], v[130:133], v[178:181], v[122:125]
	v_mfma_f32_16x16x32_bf16 v[126:129], v[138:141], v[178:181], v[126:129]
	v_mfma_f32_16x16x32_bf16 v[110:113], v[130:133], v[192:195], v[110:113]
	v_mfma_f32_16x16x32_bf16 v[106:109], v[138:141], v[192:195], v[106:109]
	v_mfma_f32_16x16x32_bf16 v[94:97], v[130:133], v[200:203], v[94:97]
	v_mfma_f32_16x16x32_bf16 v[90:93], v[138:141], v[200:203], v[90:93]
	v_mfma_f32_16x16x32_bf16 v[78:81], v[130:133], v[208:211], v[78:81]
	v_mfma_f32_16x16x32_bf16 v[74:77], v[138:141], v[208:211], v[74:77]
	v_mfma_f32_16x16x32_bf16 v[122:125], v[134:137], v[182:185], v[122:125]
	v_mfma_f32_16x16x32_bf16 v[126:129], v[154:157], v[182:185], v[126:129]
	v_mfma_f32_16x16x32_bf16 v[110:113], v[134:137], v[196:199], v[110:113]
	v_mfma_f32_16x16x32_bf16 v[106:109], v[154:157], v[196:199], v[106:109]
	v_mfma_f32_16x16x32_bf16 v[94:97], v[134:137], v[204:207], v[94:97]
	v_mfma_f32_16x16x32_bf16 v[90:93], v[154:157], v[204:207], v[90:93]
	v_mfma_f32_16x16x32_bf16 v[78:81], v[134:137], v[212:215], v[78:81]
	v_mfma_f32_16x16x32_bf16 v[74:77], v[154:157], v[212:215], v[74:77]
	s_setprio 0
	s_setprio 3
	v_mfma_f32_16x16x32_bf16 v[118:121], v[162:165], v[178:181], v[118:121]
	v_mfma_f32_16x16x32_bf16 v[114:117], v[170:173], v[178:181], v[114:117]
	v_mfma_f32_16x16x32_bf16 v[102:105], v[162:165], v[192:195], v[102:105]
	v_mfma_f32_16x16x32_bf16 v[98:101], v[170:173], v[192:195], v[98:101]
	v_mfma_f32_16x16x32_bf16 v[86:89], v[162:165], v[200:203], v[86:89]
	v_mfma_f32_16x16x32_bf16 v[82:85], v[170:173], v[200:203], v[82:85]
	v_mfma_f32_16x16x32_bf16 v[70:73], v[162:165], v[208:211], v[70:73]
	v_mfma_f32_16x16x32_bf16 v[66:69], v[170:173], v[208:211], v[66:69]
	v_mfma_f32_16x16x32_bf16 v[118:121], v[166:169], v[182:185], v[118:121]
	v_mfma_f32_16x16x32_bf16 v[114:117], v[174:177], v[182:185], v[114:117]
	v_mfma_f32_16x16x32_bf16 v[102:105], v[166:169], v[196:199], v[102:105]
	v_mfma_f32_16x16x32_bf16 v[98:101], v[174:177], v[196:199], v[98:101]
	v_mfma_f32_16x16x32_bf16 v[86:89], v[166:169], v[204:207], v[86:89]
	v_mfma_f32_16x16x32_bf16 v[82:85], v[174:177], v[204:207], v[82:85]
	v_mfma_f32_16x16x32_bf16 v[70:73], v[166:169], v[212:215], v[70:73]
	v_mfma_f32_16x16x32_bf16 v[66:69], v[174:177], v[212:215], v[66:69]
	s_setprio 0
	s_barrier
; #define PG8_STAGE(bufoff, gbase, voff) do { _Pragma("unroll") for (int _i = 0; _i < 2; ++_i) \
;         __builtin_amdgcn_global_load_lds((const unsigned*)((const char*)(gbase) + (voff)[_i]), (LAS unsigned*)(lds + (bufoff) + ldsw + _i * 8192), 16, 0, 0); } while (0)
; #define PG8_LDA(dst, b, h) do { _Pragma("unroll") for (int m = 0; m < 4; ++m) _Pragma("unroll") for (int k = 0; k < 2; ++k) dst[m][k] = *(const LAS bf16x8*)(lds + PG8_SA(b, h) + aoff + m * 2048 + k * 1024); } while (0)
; #define PG8_MMA(ai, bj, At, Bt) do { __builtin_amdgcn_s_setprio(1); _Pragma("unroll") for (int m = 0; m < 4; ++m) _Pragma("unroll") for (int n = 0; n < 2; ++n) _Pragma("unroll") for (int k = 0; k < 2; ++k) \
;         acc[ai][bj][m][n] = __builtin_amdgcn_mfma_f32_16x16x32_bf16(Bt[n][k], At[m][k], acc[ai][bj][m][n], 0, 0, 0); __builtin_amdgcn_s_setprio(0); } while (0)
; #define PG8_WAIT_V(n) asm volatile("s_waitcnt vmcnt(" #n ")" ::: "memory")
; #define PG8_WAIT_L(n) asm volatile("s_waitcnt lgkmcnt(" #n ")" ::: "memory")
; #define PG8_BAR __builtin_amdgcn_s_barrier()
; #define PG8_SCHED __builtin_amdgcn_sched_barrier(0)
; template <class Epi, class Sched>
; __device__ __forceinline__ void gemm_phase(LAS unsigned char* lds, const Gemm g, const Sched& S, const Epi& E) {
;     ...
;             PG8_LDA(At, 1, 1); PG8_STAGE(PG8_SB(1, 0), b3, voffB); PG8_STAGE(PG8_SB(1, 1), b3 + hstep, voffB); PG8_STAGE(PG8_SA(1, 0), a3, voffA);
;             PG8_WAIT_V(8); PG8_WAIT_L(0); PG8_BAR; PG8_MMA(1, 0, At, B0); PG8_MMA(1, 1, At, B1); PG8_BAR; PG8_SCHED;
;         }
	s_add_i32 s1, s1, s4
	s_add_u32 s48, s60, 0x80
	s_addc_u32 s49, s61, 0
	s_mov_b32 m0, s1
	ds_read_b128 v[178:181], v161 offset:49152
	ds_read_b128 v[182:185], v161 offset:50176
	ds_read_b128 v[192:195], v161 offset:51200
	ds_read_b128 v[196:199], v161 offset:52224
	ds_read_b128 v[200:203], v161 offset:53248
	ds_read_b128 v[204:207], v161 offset:54272
	ds_read_b128 v[208:211], v161 offset:55296
	ds_read_b128 v[212:215], v161 offset:56320
	global_load_lds_dwordx4 v0, s[48:49]
	s_add_i32 m0, s1, 0x2000
	s_add_i32 s1, s59, s4
	global_load_lds_dwordx4 v142, s[48:49]
	s_add_u32 s48, s48, s26
	s_addc_u32 s49, s49, s27
	s_mov_b32 m0, s1
	s_nop 0
	global_load_lds_dwordx4 v0, s[48:49]
	s_add_i32 m0, s1, 0x2000
	s_nop 0
	global_load_lds_dwordx4 v142, s[48:49]
	s_add_u32 s48, s52, 0x80
	s_addc_u32 s49, s53, 0
	s_mov_b32 m0, s54
	s_nop 0
	global_load_lds_dwordx4 v146, s[48:49]
	s_mov_b32 m0, s55
	s_nop 0
	global_load_lds_dwordx4 v144, s[48:49]
	s_waitcnt vmcnt(8)
	s_waitcnt lgkmcnt(0)
	s_barrier
	s_setprio 3
	s_waitcnt lgkmcnt(0)
	v_mfma_f32_16x16x32_bf16 v[62:65], v[130:133], v[178:181], v[62:65]
	v_mfma_f32_16x16x32_bf16 v[58:61], v[138:141], v[178:181], v[58:61]
	v_mfma_f32_16x16x32_bf16 v[46:49], v[130:133], v[192:195], v[46:49]
	v_mfma_f32_16x16x32_bf16 v[42:45], v[138:141], v[192:195], v[42:45]
	v_mfma_f32_16x16x32_bf16 v[30:33], v[130:133], v[200:203], v[30:33]
	v_mfma_f32_16x16x32_bf16 v[26:29], v[138:141], v[200:203], v[26:29]
	v_mfma_f32_16x16x32_bf16 v[14:17], v[130:133], v[208:211], v[14:17]
	v_mfma_f32_16x16x32_bf16 v[10:13], v[138:141], v[208:211], v[10:13]
	v_mfma_f32_16x16x32_bf16 v[62:65], v[134:137], v[182:185], v[62:65]
	v_mfma_f32_16x16x32_bf16 v[58:61], v[154:157], v[182:185], v[58:61]
	v_mfma_f32_16x16x32_bf16 v[46:49], v[134:137], v[196:199], v[46:49]
	v_mfma_f32_16x16x32_bf16 v[42:45], v[154:157], v[196:199], v[42:45]
	v_mfma_f32_16x16x32_bf16 v[30:33], v[134:137], v[204:207], v[30:33]
	v_mfma_f32_16x16x32_bf16 v[26:29], v[154:157], v[204:207], v[26:29]
	v_mfma_f32_16x16x32_bf16 v[14:17], v[134:137], v[212:215], v[14:17]
	v_mfma_f32_16x16x32_bf16 v[10:13], v[154:157], v[212:215], v[10:13]
	s_setprio 0
	s_setprio 3
	v_mfma_f32_16x16x32_bf16 v[54:57], v[162:165], v[178:181], v[54:57]
	v_mfma_f32_16x16x32_bf16 v[50:53], v[170:173], v[178:181], v[50:53]
	v_mfma_f32_16x16x32_bf16 v[38:41], v[162:165], v[192:195], v[38:41]
	v_mfma_f32_16x16x32_bf16 v[34:37], v[170:173], v[192:195], v[34:37]
	v_mfma_f32_16x16x32_bf16 v[22:25], v[162:165], v[200:203], v[22:25]
	v_mfma_f32_16x16x32_bf16 v[18:21], v[170:173], v[200:203], v[18:21]
	v_mfma_f32_16x16x32_bf16 v[6:9], v[162:165], v[208:211], v[6:9]
	v_mfma_f32_16x16x32_bf16 v[2:5], v[170:173], v[208:211], v[2:5]
	v_mfma_f32_16x16x32_bf16 v[54:57], v[166:169], v[182:185], v[54:57]
	v_mfma_f32_16x16x32_bf16 v[50:53], v[174:177], v[182:185], v[50:53]
	v_mfma_f32_16x16x32_bf16 v[38:41], v[166:169], v[196:199], v[38:41]
	v_mfma_f32_16x16x32_bf16 v[34:37], v[174:177], v[196:199], v[34:37]
	v_mfma_f32_16x16x32_bf16 v[22:25], v[166:169], v[204:207], v[22:25]
	v_mfma_f32_16x16x32_bf16 v[18:21], v[174:177], v[204:207], v[18:21]
	v_mfma_f32_16x16x32_bf16 v[6:9], v[166:169], v[212:215], v[6:9]
	v_mfma_f32_16x16x32_bf16 v[2:5], v[174:177], v[212:215], v[2:5]
	s_setprio 0
	s_barrier
	s_cmp_ge_i32 s58, s21
	s_mov_b64 s[48:49], s[50:51]
	s_mov_b32 s52, s58
	s_cbranch_scc0 .LBB0_418

; #define PG8_STAGE(bufoff, gbase, voff) do { _Pragma("unroll") for (int _i = 0; _i < 2; ++_i) \
;         __builtin_amdgcn_global_load_lds((const unsigned*)((const char*)(gbase) + (voff)[_i]), (LAS unsigned*)(lds + (bufoff) + ldsw + _i * 8192), 16, 0, 0); } while (0)
; #define PG8_LDA(dst, b, h) do { _Pragma("unroll") for (int m = 0; m < 4; ++m) _Pragma("unroll") for (int k = 0; k < 2; ++k) dst[m][k] = *(const LAS bf16x8*)(lds + PG8_SA(b, h) + aoff + m * 2048 + k * 1024); } while (0)
; #define PG8_LDB(dst, b, h) do { _Pragma("unroll") for (int n = 0; n < 2; ++n) _Pragma("unroll") for (int k = 0; k < 2; ++k) dst[n][k] = *(const LAS bf16x8*)(lds + PG8_SB(b, h) + boff + n * 2048 + k * 1024); } while (0)
; #define PG8_MMA(ai, bj, At, Bt) do { __builtin_amdgcn_s_setprio(1); _Pragma("unroll") for (int m = 0; m < 4; ++m) _Pragma("unroll") for (int n = 0; n < 2; ++n) _Pragma("unroll") for (int k = 0; k < 2; ++k) \
;         acc[ai][bj][m][n] = __builtin_amdgcn_mfma_f32_16x16x32_bf16(Bt[n][k], At[m][k], acc[ai][bj][m][n], 0, 0, 0); __builtin_amdgcn_s_setprio(0); } while (0)
; #define PG8_WAIT_V(n) asm volatile("s_waitcnt vmcnt(" #n ")" ::: "memory")
; #define PG8_WAIT_L(n) asm volatile("s_waitcnt lgkmcnt(" #n ")" ::: "memory")
; #define PG8_BAR __builtin_amdgcn_s_barrier()
; template <class Epi, class Sched>
; __device__ __forceinline__ void gemm_phase(LAS unsigned char* lds, const Gemm g, const Sched& S, const Epi& E) {
;     ...
;         for (int t = 0; t < nt; t += 2) {
;             const bool last = (t == nt - 2);
;             const char* a1 = cA + (size_t)(t + 1) * kstep;
;             const char* a2 = last ? nA : cA + (size_t)(t + 2) * kstep; const char* b2 = last ? nB : cB + (size_t)(t + 2) * kstep;
;             const char* a3 = a2 + kstep; const char* b3 = b2 + kstep;
;             if (last && has_next) S.a_ready(nxt);
;             PG8_LDB(B0, 0, 0); PG8_LDB(B1, 0, 1); PG8_SCHED; PG8_LDA(At, 0, 0); PG8_STAGE(PG8_SA(1, 1), a1 + hstep, voffA);
;             PG8_WAIT_V(8); PG8_WAIT_L(0); PG8_BAR; PG8_MMA(0, 0, At, B0); PG8_MMA(0, 1, At, B1); PG8_BAR; PG8_SCHED;
;             PG8_LDA(At, 0, 1); PG8_STAGE(PG8_SB(0, 0), b2, voffB); PG8_STAGE(PG8_SB(0, 1), b2 + hstep, voffB); PG8_STAGE(PG8_SA(0, 0), a2, voffA);
;             PG8_WAIT_V(8); PG8_WAIT_L(0); PG8_BAR; PG8_MMA(1, 0, At, B0); PG8_MMA(1, 1, At, B1); PG8_BAR; PG8_SCHED;
.LBB0_435:
	s_add_i32 s62, s52, 2
	s_add_u32 s50, s48, 0x100
	s_addc_u32 s51, s49, 0
	s_add_u32 s1, s9, s48
	s_addc_u32 s53, s36, s49
	s_cmp_eq_u32 s60, s52
	s_cselect_b32 s52, s100, s50
	s_cselect_b32 s63, 0, s51
	s_cselect_b32 s64, s46, s1
	s_cselect_b32 s65, s47, s53
	s_add_u32 s52, s2, s52
	s_addc_u32 s53, s3, s63
	s_add_i32 s1, 0, 0x10000
	s_add_i32 s63, 0, 0x14000
	v_add_u32_e32 v156, s1, v142
	v_add_u32_e32 v172, s63, v142
	ds_read_b128 v[144:147], v156
	ds_read_b128 v[148:151], v156 offset:1024
	ds_read_b128 v[152:155], v156 offset:2048
	ds_read_b128 v[156:159], v156 offset:3072
	ds_read_b128 v[160:163], v172
	ds_read_b128 v[164:167], v172 offset:1024
	ds_read_b128 v[168:171], v172 offset:2048
	ds_read_b128 v[172:175], v172 offset:3072
	s_add_u32 s48, s48, s2
	s_addc_u32 s49, s49, s3
	s_add_u32 s48, s48, s26
	s_addc_u32 s49, s49, s27
	s_add_u32 s48, s48, 0x80
	s_addc_u32 s49, s49, 0
	s_add_i32 m0, s5, 0xc000
	ds_read_b128 v[176:179], v143
	ds_read_b128 v[180:183], v143 offset:1024
	ds_read_b128 v[184:187], v143 offset:2048
	ds_read_b128 v[192:195], v143 offset:3072
	ds_read_b128 v[196:199], v143 offset:4096
	ds_read_b128 v[200:203], v143 offset:5120
	ds_read_b128 v[204:207], v143 offset:6144
	ds_read_b128 v[208:211], v143 offset:7168
	global_load_lds_dwordx4 v134, s[48:49]
	s_add_i32 m0, s5, 0xe000
	s_nop 0
	global_load_lds_dwordx4 v132, s[48:49]
	s_waitcnt vmcnt(8)
	s_waitcnt lgkmcnt(0)
	s_barrier
	s_setprio 3
	s_waitcnt lgkmcnt(0)
	v_mfma_f32_16x16x32_bf16 v[122:125], v[144:147], v[176:179], v[122:125]
	v_mfma_f32_16x16x32_bf16 v[126:129], v[152:155], v[176:179], v[126:129]
	v_mfma_f32_16x16x32_bf16 v[110:113], v[144:147], v[184:187], v[110:113]
	v_mfma_f32_16x16x32_bf16 v[106:109], v[152:155], v[184:187], v[106:109]
	v_mfma_f32_16x16x32_bf16 v[94:97], v[144:147], v[196:199], v[94:97]
	v_mfma_f32_16x16x32_bf16 v[90:93], v[152:155], v[196:199], v[90:93]
	v_mfma_f32_16x16x32_bf16 v[78:81], v[144:147], v[204:207], v[78:81]
	v_mfma_f32_16x16x32_bf16 v[74:77], v[152:155], v[204:207], v[74:77]
	v_mfma_f32_16x16x32_bf16 v[122:125], v[148:151], v[180:183], v[122:125]
	v_mfma_f32_16x16x32_bf16 v[126:129], v[156:159], v[180:183], v[126:129]
	v_mfma_f32_16x16x32_bf16 v[110:113], v[148:151], v[192:195], v[110:113]
	v_mfma_f32_16x16x32_bf16 v[106:109], v[156:159], v[192:195], v[106:109]
	v_mfma_f32_16x16x32_bf16 v[94:97], v[148:151], v[200:203], v[94:97]
	v_mfma_f32_16x16x32_bf16 v[90:93], v[156:159], v[200:203], v[90:93]
	v_mfma_f32_16x16x32_bf16 v[78:81], v[148:151], v[208:211], v[78:81]
	v_mfma_f32_16x16x32_bf16 v[74:77], v[156:159], v[208:211], v[74:77]
	s_setprio 0
	s_setprio 3
	v_mfma_f32_16x16x32_bf16 v[118:121], v[160:163], v[176:179], v[118:121]
	v_mfma_f32_16x16x32_bf16 v[114:117], v[168:171], v[176:179], v[114:117]
	v_mfma_f32_16x16x32_bf16 v[102:105], v[160:163], v[184:187], v[102:105]
	v_mfma_f32_16x16x32_bf16 v[98:101], v[168:171], v[184:187], v[98:101]
	v_mfma_f32_16x16x32_bf16 v[86:89], v[160:163], v[196:199], v[86:89]
	v_mfma_f32_16x16x32_bf16 v[82:85], v[168:171], v[196:199], v[82:85]
	v_mfma_f32_16x16x32_bf16 v[70:73], v[160:163], v[204:207], v[70:73]
	v_mfma_f32_16x16x32_bf16 v[66:69], v[168:171], v[204:207], v[66:69]
	v_mfma_f32_16x16x32_bf16 v[118:121], v[164:167], v[180:183], v[118:121]
	v_mfma_f32_16x16x32_bf16 v[114:117], v[172:175], v[180:183], v[114:117]
	v_mfma_f32_16x16x32_bf16 v[102:105], v[164:167], v[192:195], v[102:105]
	v_mfma_f32_16x16x32_bf16 v[98:101], v[172:175], v[192:195], v[98:101]
	v_mfma_f32_16x16x32_bf16 v[86:89], v[164:167], v[200:203], v[86:89]
	v_mfma_f32_16x16x32_bf16 v[82:85], v[172:175], v[200:203], v[82:85]
	v_mfma_f32_16x16x32_bf16 v[70:73], v[164:167], v[208:211], v[70:73]
	v_mfma_f32_16x16x32_bf16 v[66:69], v[172:175], v[208:211], v[66:69]
	s_setprio 0
	s_barrier
	s_add_i32 s1, s1, s4
	s_mov_b32 m0, s1
	ds_read_b128 v[176:179], v143 offset:16384
	ds_read_b128 v[180:183], v143 offset:17408
	ds_read_b128 v[184:187], v143 offset:18432
	ds_read_b128 v[192:195], v143 offset:19456
	ds_read_b128 v[196:199], v143 offset:20480
	ds_read_b128 v[200:203], v143 offset:21504
	ds_read_b128 v[204:207], v143 offset:22528
	ds_read_b128 v[208:211], v143 offset:23552
	global_load_lds_dwordx4 v0, s[64:65]
	s_add_i32 m0, s1, 0x2000
	s_add_u32 s48, s64, s26
	s_addc_u32 s49, s65, s27
	s_add_i32 s1, s63, s4
	global_load_lds_dwordx4 v130, s[64:65]
	s_mov_b32 m0, s1
	s_nop 0
	global_load_lds_dwordx4 v0, s[48:49]
	s_add_i32 m0, s1, 0x2000
	s_nop 0
	global_load_lds_dwordx4 v130, s[48:49]
	s_mov_b32 m0, s5
	s_nop 0
	global_load_lds_dwordx4 v134, s[52:53]
	s_mov_b32 m0, s54
	s_nop 0
	global_load_lds_dwordx4 v132, s[52:53]
	s_waitcnt vmcnt(8)
	s_waitcnt lgkmcnt(0)
	s_barrier
; #define PG8_STAGE(bufoff, gbase, voff) do { _Pragma("unroll") for (int _i = 0; _i < 2; ++_i) \
;         __builtin_amdgcn_global_load_lds((const unsigned*)((const char*)(gbase) + (voff)[_i]), (LAS unsigned*)(lds + (bufoff) + ldsw + _i * 8192), 16, 0, 0); } while (0)
; #define PG8_LDA(dst, b, h) do { _Pragma("unroll") for (int m = 0; m < 4; ++m) _Pragma("unroll") for (int k = 0; k < 2; ++k) dst[m][k] = *(const LAS bf16x8*)(lds + PG8_SA(b, h) + aoff + m * 2048 + k * 1024); } while (0)
; #define PG8_LDB(dst, b, h) do { _Pragma("unroll") for (int n = 0; n < 2; ++n) _Pragma("unroll") for (int k = 0; k < 2; ++k) dst[n][k] = *(const LAS bf16x8*)(lds + PG8_SB(b, h) + boff + n * 2048 + k * 1024); } while (0)
; #define PG8_MMA(ai, bj, At, Bt) do { __builtin_amdgcn_s_setprio(1); _Pragma("unroll") for (int m = 0; m < 4; ++m) _Pragma("unroll") for (int n = 0; n < 2; ++n) _Pragma("unroll") for (int k = 0; k < 2; ++k) \
;         acc[ai][bj][m][n] = __builtin_amdgcn_mfma_f32_16x16x32_bf16(Bt[n][k], At[m][k], acc[ai][bj][m][n], 0, 0, 0); __builtin_amdgcn_s_setprio(0); } while (0)
; #define PG8_WAIT_V(n) asm volatile("s_waitcnt vmcnt(" #n ")" ::: "memory")
; #define PG8_WAIT_L(n) asm volatile("s_waitcnt lgkmcnt(" #n ")" ::: "memory")
; #define PG8_BAR __builtin_amdgcn_s_barrier()
; #define PG8_SCHED __builtin_amdgcn_sched_barrier(0)
; template <class Epi, class Sched>
; __device__ __forceinline__ void gemm_phase(LAS unsigned char* lds, const Gemm g, const Sched& S, const Epi& E) {
;     ...
;             PG8_WAIT_V(8); PG8_WAIT_L(0); PG8_BAR; PG8_MMA(1, 0, At, B0); PG8_MMA(1, 1, At, B1); PG8_BAR; PG8_SCHED;
;             PG8_LDB(B0, 1, 0); PG8_LDB(B1, 1, 1); PG8_SCHED; PG8_LDA(At, 1, 0); PG8_STAGE(PG8_SA(0, 1), a2 + hstep, voffA);
;             PG8_WAIT_V(8); PG8_WAIT_L(0); PG8_BAR; PG8_MMA(0, 0, At, B0); PG8_MMA(0, 1, At, B1); PG8_BAR; PG8_SCHED;
	s_setprio 3
	s_waitcnt lgkmcnt(0)
	v_mfma_f32_16x16x32_bf16 v[62:65], v[144:147], v[176:179], v[62:65]
	v_mfma_f32_16x16x32_bf16 v[58:61], v[152:155], v[176:179], v[58:61]
	v_mfma_f32_16x16x32_bf16 v[46:49], v[144:147], v[184:187], v[46:49]
	v_mfma_f32_16x16x32_bf16 v[42:45], v[152:155], v[184:187], v[42:45]
	v_mfma_f32_16x16x32_bf16 v[30:33], v[144:147], v[196:199], v[30:33]
	v_mfma_f32_16x16x32_bf16 v[26:29], v[152:155], v[196:199], v[26:29]
	v_mfma_f32_16x16x32_bf16 v[14:17], v[144:147], v[204:207], v[14:17]
	v_mfma_f32_16x16x32_bf16 v[10:13], v[152:155], v[204:207], v[10:13]
	v_mfma_f32_16x16x32_bf16 v[62:65], v[148:151], v[180:183], v[62:65]
	v_mfma_f32_16x16x32_bf16 v[58:61], v[156:159], v[180:183], v[58:61]
	v_mfma_f32_16x16x32_bf16 v[46:49], v[148:151], v[192:195], v[46:49]
	v_mfma_f32_16x16x32_bf16 v[42:45], v[156:159], v[192:195], v[42:45]
	v_mfma_f32_16x16x32_bf16 v[30:33], v[148:151], v[200:203], v[30:33]
	v_mfma_f32_16x16x32_bf16 v[26:29], v[156:159], v[200:203], v[26:29]
	v_mfma_f32_16x16x32_bf16 v[14:17], v[148:151], v[208:211], v[14:17]
	v_mfma_f32_16x16x32_bf16 v[10:13], v[156:159], v[208:211], v[10:13]
	s_setprio 0
	s_setprio 3
	v_mfma_f32_16x16x32_bf16 v[54:57], v[160:163], v[176:179], v[54:57]
	v_mfma_f32_16x16x32_bf16 v[50:53], v[168:171], v[176:179], v[50:53]
	v_mfma_f32_16x16x32_bf16 v[38:41], v[160:163], v[184:187], v[38:41]
	v_mfma_f32_16x16x32_bf16 v[34:37], v[168:171], v[184:187], v[34:37]
	v_mfma_f32_16x16x32_bf16 v[22:25], v[160:163], v[196:199], v[22:25]
	v_mfma_f32_16x16x32_bf16 v[18:21], v[168:171], v[196:199], v[18:21]
	v_mfma_f32_16x16x32_bf16 v[6:9], v[160:163], v[204:207], v[6:9]
	v_mfma_f32_16x16x32_bf16 v[2:5], v[168:171], v[204:207], v[2:5]
	v_mfma_f32_16x16x32_bf16 v[54:57], v[164:167], v[180:183], v[54:57]
	v_mfma_f32_16x16x32_bf16 v[50:53], v[172:175], v[180:183], v[50:53]
	v_mfma_f32_16x16x32_bf16 v[38:41], v[164:167], v[192:195], v[38:41]
	v_mfma_f32_16x16x32_bf16 v[34:37], v[172:175], v[192:195], v[34:37]
	v_mfma_f32_16x16x32_bf16 v[22:25], v[164:167], v[200:203], v[22:25]
	v_mfma_f32_16x16x32_bf16 v[18:21], v[172:175], v[200:203], v[18:21]
	v_mfma_f32_16x16x32_bf16 v[6:9], v[164:167], v[208:211], v[6:9]
	v_mfma_f32_16x16x32_bf16 v[2:5], v[172:175], v[208:211], v[2:5]
	s_setprio 0
	s_barrier
	s_add_i32 s1, 0, 0x18000
	s_add_i32 s63, 0, 0x1c000
	v_add_u32_e32 v156, s1, v142
	v_add_u32_e32 v172, s63, v142
	ds_read_b128 v[144:147], v156
	ds_read_b128 v[148:151], v156 offset:1024
	ds_read_b128 v[152:155], v156 offset:2048
	ds_read_b128 v[156:159], v156 offset:3072
	ds_read_b128 v[160:163], v172
	ds_read_b128 v[164:167], v172 offset:1024
	ds_read_b128 v[168:171], v172 offset:2048
	ds_read_b128 v[172:175], v172 offset:3072
	s_add_u32 s48, s52, s26
	s_addc_u32 s49, s53, s27
	s_mov_b32 m0, s55
	ds_read_b128 v[176:179], v143 offset:32768
	ds_read_b128 v[180:183], v143 offset:33792
	ds_read_b128 v[184:187], v143 offset:34816
	ds_read_b128 v[192:195], v143 offset:35840
	ds_read_b128 v[196:199], v143 offset:36864
	ds_read_b128 v[200:203], v143 offset:37888
	ds_read_b128 v[204:207], v143 offset:38912
	ds_read_b128 v[208:211], v143 offset:39936
	global_load_lds_dwordx4 v134, s[48:49]
	s_mov_b32 m0, s56
	s_nop 0
	global_load_lds_dwordx4 v132, s[48:49]
	s_waitcnt vmcnt(8)
	s_waitcnt lgkmcnt(0)
	s_barrier
	s_setprio 3
	s_waitcnt lgkmcnt(0)
	v_mfma_f32_16x16x32_bf16 v[122:125], v[144:147], v[176:179], v[122:125]
	v_mfma_f32_16x16x32_bf16 v[126:129], v[152:155], v[176:179], v[126:129]
	v_mfma_f32_16x16x32_bf16 v[110:113], v[144:147], v[184:187], v[110:113]
	v_mfma_f32_16x16x32_bf16 v[106:109], v[152:155], v[184:187], v[106:109]
	v_mfma_f32_16x16x32_bf16 v[94:97], v[144:147], v[196:199], v[94:97]
	v_mfma_f32_16x16x32_bf16 v[90:93], v[152:155], v[196:199], v[90:93]
	v_mfma_f32_16x16x32_bf16 v[78:81], v[144:147], v[204:207], v[78:81]
	v_mfma_f32_16x16x32_bf16 v[74:77], v[152:155], v[204:207], v[74:77]
	v_mfma_f32_16x16x32_bf16 v[122:125], v[148:151], v[180:183], v[122:125]
	v_mfma_f32_16x16x32_bf16 v[126:129], v[156:159], v[180:183], v[126:129]
	v_mfma_f32_16x16x32_bf16 v[110:113], v[148:151], v[192:195], v[110:113]
	v_mfma_f32_16x16x32_bf16 v[106:109], v[156:159], v[192:195], v[106:109]
	v_mfma_f32_16x16x32_bf16 v[94:97], v[148:151], v[200:203], v[94:97]
	v_mfma_f32_16x16x32_bf16 v[90:93], v[156:159], v[200:203], v[90:93]
	v_mfma_f32_16x16x32_bf16 v[78:81], v[148:151], v[208:211], v[78:81]
	v_mfma_f32_16x16x32_bf16 v[74:77], v[156:159], v[208:211], v[74:77]
	s_setprio 0
	s_setprio 3
	v_mfma_f32_16x16x32_bf16 v[118:121], v[160:163], v[176:179], v[118:121]
	v_mfma_f32_16x16x32_bf16 v[114:117], v[168:171], v[176:179], v[114:117]
	v_mfma_f32_16x16x32_bf16 v[102:105], v[160:163], v[184:187], v[102:105]
	v_mfma_f32_16x16x32_bf16 v[98:101], v[168:171], v[184:187], v[98:101]
	v_mfma_f32_16x16x32_bf16 v[86:89], v[160:163], v[196:199], v[86:89]
	v_mfma_f32_16x16x32_bf16 v[82:85], v[168:171], v[196:199], v[82:85]
	v_mfma_f32_16x16x32_bf16 v[70:73], v[160:163], v[204:207], v[70:73]
	v_mfma_f32_16x16x32_bf16 v[66:69], v[168:171], v[204:207], v[66:69]
	v_mfma_f32_16x16x32_bf16 v[118:121], v[164:167], v[180:183], v[118:121]
	v_mfma_f32_16x16x32_bf16 v[114:117], v[172:175], v[180:183], v[114:117]
	v_mfma_f32_16x16x32_bf16 v[102:105], v[164:167], v[192:195], v[102:105]
	v_mfma_f32_16x16x32_bf16 v[98:101], v[172:175], v[192:195], v[98:101]
	v_mfma_f32_16x16x32_bf16 v[86:89], v[164:167], v[200:203], v[86:89]
	v_mfma_f32_16x16x32_bf16 v[82:85], v[172:175], v[200:203], v[82:85]
	v_mfma_f32_16x16x32_bf16 v[70:73], v[164:167], v[208:211], v[70:73]
	v_mfma_f32_16x16x32_bf16 v[66:69], v[172:175], v[208:211], v[66:69]
	s_setprio 0
	s_barrier
; #define PG8_STAGE(bufoff, gbase, voff) do { _Pragma("unroll") for (int _i = 0; _i < 2; ++_i) \
;         __builtin_amdgcn_global_load_lds((const unsigned*)((const char*)(gbase) + (voff)[_i]), (LAS unsigned*)(lds + (bufoff) + ldsw + _i * 8192), 16, 0, 0); } while (0)
; #define PG8_LDA(dst, b, h) do { _Pragma("unroll") for (int m = 0; m < 4; ++m) _Pragma("unroll") for (int k = 0; k < 2; ++k) dst[m][k] = *(const LAS bf16x8*)(lds + PG8_SA(b, h) + aoff + m * 2048 + k * 1024); } while (0)
; #define PG8_MMA(ai, bj, At, Bt) do { __builtin_amdgcn_s_setprio(1); _Pragma("unroll") for (int m = 0; m < 4; ++m) _Pragma("unroll") for (int n = 0; n < 2; ++n) _Pragma("unroll") for (int k = 0; k < 2; ++k) \
;         acc[ai][bj][m][n] = __builtin_amdgcn_mfma_f32_16x16x32_bf16(Bt[n][k], At[m][k], acc[ai][bj][m][n], 0, 0, 0); __builtin_amdgcn_s_setprio(0); } while (0)
; #define PG8_WAIT_V(n) asm volatile("s_waitcnt vmcnt(" #n ")" ::: "memory")
; #define PG8_WAIT_L(n) asm volatile("s_waitcnt lgkmcnt(" #n ")" ::: "memory")
; #define PG8_BAR __builtin_amdgcn_s_barrier()
; #define PG8_SCHED __builtin_amdgcn_sched_barrier(0)
; template <class Epi, class Sched>
; __device__ __forceinline__ void gemm_phase(LAS unsigned char* lds, const Gemm g, const Sched& S, const Epi& E) {
;     ...
;             PG8_LDA(At, 1, 1); PG8_STAGE(PG8_SB(1, 0), b3, voffB); PG8_STAGE(PG8_SB(1, 1), b3 + hstep, voffB); PG8_STAGE(PG8_SA(1, 0), a3, voffA);
;             PG8_WAIT_V(8); PG8_WAIT_L(0); PG8_BAR; PG8_MMA(1, 0, At, B0); PG8_MMA(1, 1, At, B1); PG8_BAR; PG8_SCHED;
;         }
	s_add_i32 s1, s1, s4
	s_add_u32 s48, s64, 0x80
	s_addc_u32 s49, s65, 0
	s_mov_b32 m0, s1
	ds_read_b128 v[176:179], v143 offset:49152
	ds_read_b128 v[180:183], v143 offset:50176
	ds_read_b128 v[184:187], v143 offset:51200
	ds_read_b128 v[192:195], v143 offset:52224
	ds_read_b128 v[196:199], v143 offset:53248
	ds_read_b128 v[200:203], v143 offset:54272
	ds_read_b128 v[204:207], v143 offset:55296
	ds_read_b128 v[208:211], v143 offset:56320
	global_load_lds_dwordx4 v0, s[48:49]
	s_add_i32 m0, s1, 0x2000
	s_add_i32 s1, s63, s4
	global_load_lds_dwordx4 v130, s[48:49]
	s_add_u32 s48, s48, s26
	s_addc_u32 s49, s49, s27
	s_mov_b32 m0, s1
	s_nop 0
	global_load_lds_dwordx4 v0, s[48:49]
	s_add_i32 m0, s1, 0x2000
	s_nop 0
	global_load_lds_dwordx4 v130, s[48:49]
	s_add_u32 s48, s52, 0x80
	s_addc_u32 s49, s53, 0
	s_mov_b32 m0, s57
	s_nop 0
	global_load_lds_dwordx4 v134, s[48:49]
	s_mov_b32 m0, s58
	s_nop 0
	global_load_lds_dwordx4 v132, s[48:49]
	s_waitcnt vmcnt(8)
	s_waitcnt lgkmcnt(0)
	s_barrier
	s_setprio 3
	s_waitcnt lgkmcnt(0)
	v_mfma_f32_16x16x32_bf16 v[62:65], v[144:147], v[176:179], v[62:65]
	v_mfma_f32_16x16x32_bf16 v[58:61], v[152:155], v[176:179], v[58:61]
	v_mfma_f32_16x16x32_bf16 v[46:49], v[144:147], v[184:187], v[46:49]
	v_mfma_f32_16x16x32_bf16 v[42:45], v[152:155], v[184:187], v[42:45]
	v_mfma_f32_16x16x32_bf16 v[30:33], v[144:147], v[196:199], v[30:33]
	v_mfma_f32_16x16x32_bf16 v[26:29], v[152:155], v[196:199], v[26:29]
	v_mfma_f32_16x16x32_bf16 v[14:17], v[144:147], v[204:207], v[14:17]
	v_mfma_f32_16x16x32_bf16 v[10:13], v[152:155], v[204:207], v[10:13]
	v_mfma_f32_16x16x32_bf16 v[62:65], v[148:151], v[180:183], v[62:65]
	v_mfma_f32_16x16x32_bf16 v[58:61], v[156:159], v[180:183], v[58:61]
	v_mfma_f32_16x16x32_bf16 v[46:49], v[148:151], v[192:195], v[46:49]
	v_mfma_f32_16x16x32_bf16 v[42:45], v[156:159], v[192:195], v[42:45]
	v_mfma_f32_16x16x32_bf16 v[30:33], v[148:151], v[200:203], v[30:33]
	v_mfma_f32_16x16x32_bf16 v[26:29], v[156:159], v[200:203], v[26:29]
	v_mfma_f32_16x16x32_bf16 v[14:17], v[148:151], v[208:211], v[14:17]
	v_mfma_f32_16x16x32_bf16 v[10:13], v[156:159], v[208:211], v[10:13]
	s_setprio 0
	s_setprio 3
	v_mfma_f32_16x16x32_bf16 v[54:57], v[160:163], v[176:179], v[54:57]
	v_mfma_f32_16x16x32_bf16 v[50:53], v[168:171], v[176:179], v[50:53]
	v_mfma_f32_16x16x32_bf16 v[38:41], v[160:163], v[184:187], v[38:41]
	v_mfma_f32_16x16x32_bf16 v[34:37], v[168:171], v[184:187], v[34:37]
	v_mfma_f32_16x16x32_bf16 v[22:25], v[160:163], v[196:199], v[22:25]
	v_mfma_f32_16x16x32_bf16 v[18:21], v[168:171], v[196:199], v[18:21]
	v_mfma_f32_16x16x32_bf16 v[6:9], v[160:163], v[204:207], v[6:9]
	v_mfma_f32_16x16x32_bf16 v[2:5], v[168:171], v[204:207], v[2:5]
	v_mfma_f32_16x16x32_bf16 v[54:57], v[164:167], v[180:183], v[54:57]
	v_mfma_f32_16x16x32_bf16 v[50:53], v[172:175], v[180:183], v[50:53]
	v_mfma_f32_16x16x32_bf16 v[38:41], v[164:167], v[192:195], v[38:41]
	v_mfma_f32_16x16x32_bf16 v[34:37], v[172:175], v[192:195], v[34:37]
	v_mfma_f32_16x16x32_bf16 v[22:25], v[164:167], v[200:203], v[22:25]
	v_mfma_f32_16x16x32_bf16 v[18:21], v[172:175], v[200:203], v[18:21]
	v_mfma_f32_16x16x32_bf16 v[6:9], v[164:167], v[208:211], v[6:9]
	v_mfma_f32_16x16x32_bf16 v[2:5], v[172:175], v[208:211], v[2:5]
	s_setprio 0
	s_barrier
	s_cmp_ge_i32 s62, s59
	s_mov_b64 s[48:49], s[50:51]
	s_mov_b32 s52, s62
	s_cbranch_scc0 .LBB0_435

; #define PG8_STAGE(bufoff, gbase, voff) do { _Pragma("unroll") for (int _i = 0; _i < 2; ++_i) \
;         __builtin_amdgcn_global_load_lds((const unsigned*)((const char*)(gbase) + (voff)[_i]), (LAS unsigned*)(lds + (bufoff) + ldsw + _i * 8192), 16, 0, 0); } while (0)
; #define PG8_LDA(dst, b, h) do { _Pragma("unroll") for (int m = 0; m < 4; ++m) _Pragma("unroll") for (int k = 0; k < 2; ++k) dst[m][k] = *(const LAS bf16x8*)(lds + PG8_SA(b, h) + aoff + m * 2048 + k * 1024); } while (0)
; #define PG8_LDB(dst, b, h) do { _Pragma("unroll") for (int n = 0; n < 2; ++n) _Pragma("unroll") for (int k = 0; k < 2; ++k) dst[n][k] = *(const LAS bf16x8*)(lds + PG8_SB(b, h) + boff + n * 2048 + k * 1024); } while (0)
; #define PG8_MMA(ai, bj, At, Bt) do { __builtin_amdgcn_s_setprio(1); _Pragma("unroll") for (int m = 0; m < 4; ++m) _Pragma("unroll") for (int n = 0; n < 2; ++n) _Pragma("unroll") for (int k = 0; k < 2; ++k) \
;         acc[ai][bj][m][n] = __builtin_amdgcn_mfma_f32_16x16x32_bf16(Bt[n][k], At[m][k], acc[ai][bj][m][n], 0, 0, 0); __builtin_amdgcn_s_setprio(0); } while (0)
; #define PG8_WAIT_V(n) asm volatile("s_waitcnt vmcnt(" #n ")" ::: "memory")
; #define PG8_WAIT_L(n) asm volatile("s_waitcnt lgkmcnt(" #n ")" ::: "memory")
; #define PG8_BAR __builtin_amdgcn_s_barrier()
; template <class Epi, class Sched>
; __device__ __forceinline__ void gemm_phase(LAS unsigned char* lds, const Gemm g, const Sched& S, const Epi& E) {
;     ...
;         for (int t = 0; t < nt; t += 2) {
;             const bool last = (t == nt - 2);
;             const char* a1 = cA + (size_t)(t + 1) * kstep;
;             const char* a2 = last ? nA : cA + (size_t)(t + 2) * kstep; const char* b2 = last ? nB : cB + (size_t)(t + 2) * kstep;
;             const char* a3 = a2 + kstep; const char* b3 = b2 + kstep;
;             if (last && has_next) S.a_ready(nxt);
;             PG8_LDB(B0, 0, 0); PG8_LDB(B1, 0, 1); PG8_SCHED; PG8_LDA(At, 0, 0); PG8_STAGE(PG8_SA(1, 1), a1 + hstep, voffA);
;             PG8_WAIT_V(8); PG8_WAIT_L(0); PG8_BAR; PG8_MMA(0, 0, At, B0); PG8_MMA(0, 1, At, B1); PG8_BAR; PG8_SCHED;
;             PG8_LDA(At, 0, 1); PG8_STAGE(PG8_SB(0, 0), b2, voffB); PG8_STAGE(PG8_SB(0, 1), b2 + hstep, voffB); PG8_STAGE(PG8_SA(0, 0), a2, voffA);
;             PG8_WAIT_V(8); PG8_WAIT_L(0); PG8_BAR; PG8_MMA(1, 0, At, B0); PG8_MMA(1, 1, At, B1); PG8_BAR; PG8_SCHED;
.LBB0_450:
	s_add_i32 s60, s50, 2
	s_add_u32 s48, s46, 0x100
	s_addc_u32 s49, s47, 0
	s_add_u32 s1, s9, s46
	s_addc_u32 s51, s36, s47
	s_cmp_eq_u32 s58, s50
	s_cselect_b32 s50, 0xff000000, s48
	s_cselect_b32 s61, -1, s49
	s_cselect_b32 s62, s44, s1
	s_cselect_b32 s63, s45, s51
	s_add_u32 s50, s2, s50
	s_addc_u32 s51, s3, s61
	s_add_i32 s1, 0, 0x10000
	s_add_i32 s61, 0, 0x14000
	v_add_u32_e32 v154, s1, v160
	v_add_u32_e32 v158, s61, v160
	ds_read_b128 v[130:133], v154
	ds_read_b128 v[134:137], v154 offset:1024
	ds_read_b128 v[138:141], v154 offset:2048
	ds_read_b128 v[154:157], v154 offset:3072
	ds_read_b128 v[162:165], v158
	ds_read_b128 v[166:169], v158 offset:1024
	ds_read_b128 v[170:173], v158 offset:2048
	ds_read_b128 v[174:177], v158 offset:3072
	s_add_u32 s46, s46, s2
	s_addc_u32 s47, s47, s3
	s_add_u32 s46, s46, s18
	s_addc_u32 s47, s47, s19
	s_add_u32 s46, s46, 0x80
	s_addc_u32 s47, s47, 0
	s_add_i32 m0, s5, 0xc000
	ds_read_b128 v[178:181], v161
	ds_read_b128 v[182:185], v161 offset:1024
	ds_read_b128 v[192:195], v161 offset:2048
	ds_read_b128 v[196:199], v161 offset:3072
	ds_read_b128 v[200:203], v161 offset:4096
	ds_read_b128 v[204:207], v161 offset:5120
	ds_read_b128 v[208:211], v161 offset:6144
	ds_read_b128 v[212:215], v161 offset:7168
	global_load_lds_dwordx4 v146, s[46:47]
	s_add_i32 m0, s5, 0xe000
	s_nop 0
	global_load_lds_dwordx4 v144, s[46:47]
	s_waitcnt vmcnt(8)
	s_waitcnt lgkmcnt(0)
	s_barrier
	s_setprio 3
	s_waitcnt lgkmcnt(0)
	v_mfma_f32_16x16x32_bf16 v[122:125], v[130:133], v[178:181], v[122:125]
	v_mfma_f32_16x16x32_bf16 v[126:129], v[138:141], v[178:181], v[126:129]
	v_mfma_f32_16x16x32_bf16 v[110:113], v[130:133], v[192:195], v[110:113]
	v_mfma_f32_16x16x32_bf16 v[106:109], v[138:141], v[192:195], v[106:109]
	v_mfma_f32_16x16x32_bf16 v[94:97], v[130:133], v[200:203], v[94:97]
	v_mfma_f32_16x16x32_bf16 v[90:93], v[138:141], v[200:203], v[90:93]
	v_mfma_f32_16x16x32_bf16 v[78:81], v[130:133], v[208:211], v[78:81]
	v_mfma_f32_16x16x32_bf16 v[74:77], v[138:141], v[208:211], v[74:77]
	v_mfma_f32_16x16x32_bf16 v[122:125], v[134:137], v[182:185], v[122:125]
	v_mfma_f32_16x16x32_bf16 v[126:129], v[154:157], v[182:185], v[126:129]
	v_mfma_f32_16x16x32_bf16 v[110:113], v[134:137], v[196:199], v[110:113]
	v_mfma_f32_16x16x32_bf16 v[106:109], v[154:157], v[196:199], v[106:109]
	v_mfma_f32_16x16x32_bf16 v[94:97], v[134:137], v[204:207], v[94:97]
	v_mfma_f32_16x16x32_bf16 v[90:93], v[154:157], v[204:207], v[90:93]
	v_mfma_f32_16x16x32_bf16 v[78:81], v[134:137], v[212:215], v[78:81]
	v_mfma_f32_16x16x32_bf16 v[74:77], v[154:157], v[212:215], v[74:77]
	s_setprio 0
	s_setprio 3
	v_mfma_f32_16x16x32_bf16 v[118:121], v[162:165], v[178:181], v[118:121]
	v_mfma_f32_16x16x32_bf16 v[114:117], v[170:173], v[178:181], v[114:117]
	v_mfma_f32_16x16x32_bf16 v[102:105], v[162:165], v[192:195], v[102:105]
	v_mfma_f32_16x16x32_bf16 v[98:101], v[170:173], v[192:195], v[98:101]
	v_mfma_f32_16x16x32_bf16 v[86:89], v[162:165], v[200:203], v[86:89]
	v_mfma_f32_16x16x32_bf16 v[82:85], v[170:173], v[200:203], v[82:85]
	v_mfma_f32_16x16x32_bf16 v[70:73], v[162:165], v[208:211], v[70:73]
	v_mfma_f32_16x16x32_bf16 v[66:69], v[170:173], v[208:211], v[66:69]
	v_mfma_f32_16x16x32_bf16 v[118:121], v[166:169], v[182:185], v[118:121]
	v_mfma_f32_16x16x32_bf16 v[114:117], v[174:177], v[182:185], v[114:117]
	v_mfma_f32_16x16x32_bf16 v[102:105], v[166:169], v[196:199], v[102:105]
	v_mfma_f32_16x16x32_bf16 v[98:101], v[174:177], v[196:199], v[98:101]
	v_mfma_f32_16x16x32_bf16 v[86:89], v[166:169], v[204:207], v[86:89]
	v_mfma_f32_16x16x32_bf16 v[82:85], v[174:177], v[204:207], v[82:85]
	v_mfma_f32_16x16x32_bf16 v[70:73], v[166:169], v[212:215], v[70:73]
	v_mfma_f32_16x16x32_bf16 v[66:69], v[174:177], v[212:215], v[66:69]
	s_setprio 0
	s_barrier
	s_add_i32 s1, s1, s4
	s_mov_b32 m0, s1
	ds_read_b128 v[178:181], v161 offset:16384
	ds_read_b128 v[182:185], v161 offset:17408
	ds_read_b128 v[192:195], v161 offset:18432
	ds_read_b128 v[196:199], v161 offset:19456
	ds_read_b128 v[200:203], v161 offset:20480
	ds_read_b128 v[204:207], v161 offset:21504
	ds_read_b128 v[208:211], v161 offset:22528
	ds_read_b128 v[212:215], v161 offset:23552
	global_load_lds_dwordx4 v0, s[62:63]
	s_add_i32 m0, s1, 0x2000
	s_add_u32 s46, s62, s18
	s_addc_u32 s47, s63, s19
	s_add_i32 s1, s61, s4
	global_load_lds_dwordx4 v142, s[62:63]
	s_mov_b32 m0, s1
	s_nop 0
	global_load_lds_dwordx4 v0, s[46:47]
	s_add_i32 m0, s1, 0x2000
	s_nop 0
	global_load_lds_dwordx4 v142, s[46:47]
	s_mov_b32 m0, s5
	s_nop 0
	global_load_lds_dwordx4 v146, s[50:51]
	s_mov_b32 m0, s52
	s_nop 0
	global_load_lds_dwordx4 v144, s[50:51]
	s_waitcnt vmcnt(8)
	s_waitcnt lgkmcnt(0)
	s_barrier
; #define PG8_STAGE(bufoff, gbase, voff) do { _Pragma("unroll") for (int _i = 0; _i < 2; ++_i) \
;         __builtin_amdgcn_global_load_lds((const unsigned*)((const char*)(gbase) + (voff)[_i]), (LAS unsigned*)(lds + (bufoff) + ldsw + _i * 8192), 16, 0, 0); } while (0)
; #define PG8_LDA(dst, b, h) do { _Pragma("unroll") for (int m = 0; m < 4; ++m) _Pragma("unroll") for (int k = 0; k < 2; ++k) dst[m][k] = *(const LAS bf16x8*)(lds + PG8_SA(b, h) + aoff + m * 2048 + k * 1024); } while (0)
; #define PG8_LDB(dst, b, h) do { _Pragma("unroll") for (int n = 0; n < 2; ++n) _Pragma("unroll") for (int k = 0; k < 2; ++k) dst[n][k] = *(const LAS bf16x8*)(lds + PG8_SB(b, h) + boff + n * 2048 + k * 1024); } while (0)
; #define PG8_MMA(ai, bj, At, Bt) do { __builtin_amdgcn_s_setprio(1); _Pragma("unroll") for (int m = 0; m < 4; ++m) _Pragma("unroll") for (int n = 0; n < 2; ++n) _Pragma("unroll") for (int k = 0; k < 2; ++k) \
;         acc[ai][bj][m][n] = __builtin_amdgcn_mfma_f32_16x16x32_bf16(Bt[n][k], At[m][k], acc[ai][bj][m][n], 0, 0, 0); __builtin_amdgcn_s_setprio(0); } while (0)
; #define PG8_WAIT_V(n) asm volatile("s_waitcnt vmcnt(" #n ")" ::: "memory")
; #define PG8_WAIT_L(n) asm volatile("s_waitcnt lgkmcnt(" #n ")" ::: "memory")
; #define PG8_BAR __builtin_amdgcn_s_barrier()
; #define PG8_SCHED __builtin_amdgcn_sched_barrier(0)
; template <class Epi, class Sched>
; __device__ __forceinline__ void gemm_phase(LAS unsigned char* lds, const Gemm g, const Sched& S, const Epi& E) {
;     ...
;             PG8_WAIT_V(8); PG8_WAIT_L(0); PG8_BAR; PG8_MMA(1, 0, At, B0); PG8_MMA(1, 1, At, B1); PG8_BAR; PG8_SCHED;
;             PG8_LDB(B0, 1, 0); PG8_LDB(B1, 1, 1); PG8_SCHED; PG8_LDA(At, 1, 0); PG8_STAGE(PG8_SA(0, 1), a2 + hstep, voffA);
;             PG8_WAIT_V(8); PG8_WAIT_L(0); PG8_BAR; PG8_MMA(0, 0, At, B0); PG8_MMA(0, 1, At, B1); PG8_BAR; PG8_SCHED;
	s_setprio 3
	s_waitcnt lgkmcnt(0)
	v_mfma_f32_16x16x32_bf16 v[62:65], v[130:133], v[178:181], v[62:65]
	v_mfma_f32_16x16x32_bf16 v[58:61], v[138:141], v[178:181], v[58:61]
	v_mfma_f32_16x16x32_bf16 v[46:49], v[130:133], v[192:195], v[46:49]
	v_mfma_f32_16x16x32_bf16 v[42:45], v[138:141], v[192:195], v[42:45]
	v_mfma_f32_16x16x32_bf16 v[30:33], v[130:133], v[200:203], v[30:33]
	v_mfma_f32_16x16x32_bf16 v[26:29], v[138:141], v[200:203], v[26:29]
	v_mfma_f32_16x16x32_bf16 v[14:17], v[130:133], v[208:211], v[14:17]
	v_mfma_f32_16x16x32_bf16 v[10:13], v[138:141], v[208:211], v[10:13]
	v_mfma_f32_16x16x32_bf16 v[62:65], v[134:137], v[182:185], v[62:65]
	v_mfma_f32_16x16x32_bf16 v[58:61], v[154:157], v[182:185], v[58:61]
	v_mfma_f32_16x16x32_bf16 v[46:49], v[134:137], v[196:199], v[46:49]
	v_mfma_f32_16x16x32_bf16 v[42:45], v[154:157], v[196:199], v[42:45]
	v_mfma_f32_16x16x32_bf16 v[30:33], v[134:137], v[204:207], v[30:33]
	v_mfma_f32_16x16x32_bf16 v[26:29], v[154:157], v[204:207], v[26:29]
	v_mfma_f32_16x16x32_bf16 v[14:17], v[134:137], v[212:215], v[14:17]
	v_mfma_f32_16x16x32_bf16 v[10:13], v[154:157], v[212:215], v[10:13]
	s_setprio 0
	s_setprio 3
	v_mfma_f32_16x16x32_bf16 v[54:57], v[162:165], v[178:181], v[54:57]
	v_mfma_f32_16x16x32_bf16 v[50:53], v[170:173], v[178:181], v[50:53]
	v_mfma_f32_16x16x32_bf16 v[38:41], v[162:165], v[192:195], v[38:41]
	v_mfma_f32_16x16x32_bf16 v[34:37], v[170:173], v[192:195], v[34:37]
	v_mfma_f32_16x16x32_bf16 v[22:25], v[162:165], v[200:203], v[22:25]
	v_mfma_f32_16x16x32_bf16 v[18:21], v[170:173], v[200:203], v[18:21]
	v_mfma_f32_16x16x32_bf16 v[6:9], v[162:165], v[208:211], v[6:9]
	v_mfma_f32_16x16x32_bf16 v[2:5], v[170:173], v[208:211], v[2:5]
	v_mfma_f32_16x16x32_bf16 v[54:57], v[166:169], v[182:185], v[54:57]
	v_mfma_f32_16x16x32_bf16 v[50:53], v[174:177], v[182:185], v[50:53]
	v_mfma_f32_16x16x32_bf16 v[38:41], v[166:169], v[196:199], v[38:41]
	v_mfma_f32_16x16x32_bf16 v[34:37], v[174:177], v[196:199], v[34:37]
	v_mfma_f32_16x16x32_bf16 v[22:25], v[166:169], v[204:207], v[22:25]
	v_mfma_f32_16x16x32_bf16 v[18:21], v[174:177], v[204:207], v[18:21]
	v_mfma_f32_16x16x32_bf16 v[6:9], v[166:169], v[212:215], v[6:9]
	v_mfma_f32_16x16x32_bf16 v[2:5], v[174:177], v[212:215], v[2:5]
	s_setprio 0
	s_barrier
	s_add_i32 s1, 0, 0x18000
	s_add_i32 s61, 0, 0x1c000
	v_add_u32_e32 v154, s1, v160
	v_add_u32_e32 v174, s61, v160
	ds_read_b128 v[130:133], v154
	ds_read_b128 v[134:137], v154 offset:1024
	ds_read_b128 v[138:141], v154 offset:2048
	ds_read_b128 v[154:157], v154 offset:3072
	ds_read_b128 v[162:165], v174
	ds_read_b128 v[166:169], v174 offset:1024
	ds_read_b128 v[170:173], v174 offset:2048
	ds_read_b128 v[174:177], v174 offset:3072
	s_add_u32 s46, s50, s18
	s_addc_u32 s47, s51, s19
	s_mov_b32 m0, s53
	ds_read_b128 v[178:181], v161 offset:32768
	ds_read_b128 v[182:185], v161 offset:33792
	ds_read_b128 v[192:195], v161 offset:34816
	ds_read_b128 v[196:199], v161 offset:35840
	ds_read_b128 v[200:203], v161 offset:36864
	ds_read_b128 v[204:207], v161 offset:37888
	ds_read_b128 v[208:211], v161 offset:38912
	ds_read_b128 v[212:215], v161 offset:39936
	global_load_lds_dwordx4 v146, s[46:47]
	s_mov_b32 m0, s54
	s_nop 0
	global_load_lds_dwordx4 v144, s[46:47]
	s_waitcnt vmcnt(8)
	s_waitcnt lgkmcnt(0)
	s_barrier
	s_setprio 3
	s_waitcnt lgkmcnt(0)
	v_mfma_f32_16x16x32_bf16 v[122:125], v[130:133], v[178:181], v[122:125]
	v_mfma_f32_16x16x32_bf16 v[126:129], v[138:141], v[178:181], v[126:129]
	v_mfma_f32_16x16x32_bf16 v[110:113], v[130:133], v[192:195], v[110:113]
	v_mfma_f32_16x16x32_bf16 v[106:109], v[138:141], v[192:195], v[106:109]
	v_mfma_f32_16x16x32_bf16 v[94:97], v[130:133], v[200:203], v[94:97]
	v_mfma_f32_16x16x32_bf16 v[90:93], v[138:141], v[200:203], v[90:93]
	v_mfma_f32_16x16x32_bf16 v[78:81], v[130:133], v[208:211], v[78:81]
	v_mfma_f32_16x16x32_bf16 v[74:77], v[138:141], v[208:211], v[74:77]
	v_mfma_f32_16x16x32_bf16 v[122:125], v[134:137], v[182:185], v[122:125]
	v_mfma_f32_16x16x32_bf16 v[126:129], v[154:157], v[182:185], v[126:129]
	v_mfma_f32_16x16x32_bf16 v[110:113], v[134:137], v[196:199], v[110:113]
	v_mfma_f32_16x16x32_bf16 v[106:109], v[154:157], v[196:199], v[106:109]
	v_mfma_f32_16x16x32_bf16 v[94:97], v[134:137], v[204:207], v[94:97]
	v_mfma_f32_16x16x32_bf16 v[90:93], v[154:157], v[204:207], v[90:93]
	v_mfma_f32_16x16x32_bf16 v[78:81], v[134:137], v[212:215], v[78:81]
	v_mfma_f32_16x16x32_bf16 v[74:77], v[154:157], v[212:215], v[74:77]
	s_setprio 0
	s_setprio 3
	v_mfma_f32_16x16x32_bf16 v[118:121], v[162:165], v[178:181], v[118:121]
	v_mfma_f32_16x16x32_bf16 v[114:117], v[170:173], v[178:181], v[114:117]
	v_mfma_f32_16x16x32_bf16 v[102:105], v[162:165], v[192:195], v[102:105]
	v_mfma_f32_16x16x32_bf16 v[98:101], v[170:173], v[192:195], v[98:101]
	v_mfma_f32_16x16x32_bf16 v[86:89], v[162:165], v[200:203], v[86:89]
	v_mfma_f32_16x16x32_bf16 v[82:85], v[170:173], v[200:203], v[82:85]
	v_mfma_f32_16x16x32_bf16 v[70:73], v[162:165], v[208:211], v[70:73]
	v_mfma_f32_16x16x32_bf16 v[66:69], v[170:173], v[208:211], v[66:69]
	v_mfma_f32_16x16x32_bf16 v[118:121], v[166:169], v[182:185], v[118:121]
	v_mfma_f32_16x16x32_bf16 v[114:117], v[174:177], v[182:185], v[114:117]
	v_mfma_f32_16x16x32_bf16 v[102:105], v[166:169], v[196:199], v[102:105]
	v_mfma_f32_16x16x32_bf16 v[98:101], v[174:177], v[196:199], v[98:101]
	v_mfma_f32_16x16x32_bf16 v[86:89], v[166:169], v[204:207], v[86:89]
	v_mfma_f32_16x16x32_bf16 v[82:85], v[174:177], v[204:207], v[82:85]
	v_mfma_f32_16x16x32_bf16 v[70:73], v[166:169], v[212:215], v[70:73]
	v_mfma_f32_16x16x32_bf16 v[66:69], v[174:177], v[212:215], v[66:69]
	s_setprio 0
	s_barrier
; #define PG8_STAGE(bufoff, gbase, voff) do { _Pragma("unroll") for (int _i = 0; _i < 2; ++_i) \
;         __builtin_amdgcn_global_load_lds((const unsigned*)((const char*)(gbase) + (voff)[_i]), (LAS unsigned*)(lds + (bufoff) + ldsw + _i * 8192), 16, 0, 0); } while (0)
; #define PG8_LDA(dst, b, h) do { _Pragma("unroll") for (int m = 0; m < 4; ++m) _Pragma("unroll") for (int k = 0; k < 2; ++k) dst[m][k] = *(const LAS bf16x8*)(lds + PG8_SA(b, h) + aoff + m * 2048 + k * 1024); } while (0)
; #define PG8_MMA(ai, bj, At, Bt) do { __builtin_amdgcn_s_setprio(1); _Pragma("unroll") for (int m = 0; m < 4; ++m) _Pragma("unroll") for (int n = 0; n < 2; ++n) _Pragma("unroll") for (int k = 0; k < 2; ++k) \
;         acc[ai][bj][m][n] = __builtin_amdgcn_mfma_f32_16x16x32_bf16(Bt[n][k], At[m][k], acc[ai][bj][m][n], 0, 0, 0); __builtin_amdgcn_s_setprio(0); } while (0)
; #define PG8_WAIT_V(n) asm volatile("s_waitcnt vmcnt(" #n ")" ::: "memory")
; #define PG8_WAIT_L(n) asm volatile("s_waitcnt lgkmcnt(" #n ")" ::: "memory")
; #define PG8_BAR __builtin_amdgcn_s_barrier()
; #define PG8_SCHED __builtin_amdgcn_sched_barrier(0)
; template <class Epi, class Sched>
; __device__ __forceinline__ void gemm_phase(LAS unsigned char* lds, const Gemm g, const Sched& S, const Epi& E) {
;     ...
;             PG8_LDA(At, 1, 1); PG8_STAGE(PG8_SB(1, 0), b3, voffB); PG8_STAGE(PG8_SB(1, 1), b3 + hstep, voffB); PG8_STAGE(PG8_SA(1, 0), a3, voffA);
;             PG8_WAIT_V(8); PG8_WAIT_L(0); PG8_BAR; PG8_MMA(1, 0, At, B0); PG8_MMA(1, 1, At, B1); PG8_BAR; PG8_SCHED;
;         }
	s_add_i32 s1, s1, s4
	s_add_u32 s46, s62, 0x80
	s_addc_u32 s47, s63, 0
	s_mov_b32 m0, s1
	ds_read_b128 v[178:181], v161 offset:49152
	ds_read_b128 v[182:185], v161 offset:50176
	ds_read_b128 v[192:195], v161 offset:51200
	ds_read_b128 v[196:199], v161 offset:52224
	ds_read_b128 v[200:203], v161 offset:53248
	ds_read_b128 v[204:207], v161 offset:54272
	ds_read_b128 v[208:211], v161 offset:55296
	ds_read_b128 v[212:215], v161 offset:56320
	global_load_lds_dwordx4 v0, s[46:47]
	s_add_i32 m0, s1, 0x2000
	s_add_i32 s1, s61, s4
	global_load_lds_dwordx4 v142, s[46:47]
	s_add_u32 s46, s46, s18
	s_addc_u32 s47, s47, s19
	s_mov_b32 m0, s1
	s_nop 0
	global_load_lds_dwordx4 v0, s[46:47]
	s_add_i32 m0, s1, 0x2000
	s_nop 0
	global_load_lds_dwordx4 v142, s[46:47]
	s_add_u32 s46, s50, 0x80
	s_addc_u32 s47, s51, 0
	s_mov_b32 m0, s55
	s_nop 0
	global_load_lds_dwordx4 v146, s[46:47]
	s_mov_b32 m0, s56
	s_nop 0
	global_load_lds_dwordx4 v144, s[46:47]
	s_waitcnt vmcnt(8)
	s_waitcnt lgkmcnt(0)
	s_barrier
	s_setprio 3
	s_waitcnt lgkmcnt(0)
	v_mfma_f32_16x16x32_bf16 v[62:65], v[130:133], v[178:181], v[62:65]
	v_mfma_f32_16x16x32_bf16 v[58:61], v[138:141], v[178:181], v[58:61]
	v_mfma_f32_16x16x32_bf16 v[46:49], v[130:133], v[192:195], v[46:49]
	v_mfma_f32_16x16x32_bf16 v[42:45], v[138:141], v[192:195], v[42:45]
	v_mfma_f32_16x16x32_bf16 v[30:33], v[130:133], v[200:203], v[30:33]
	v_mfma_f32_16x16x32_bf16 v[26:29], v[138:141], v[200:203], v[26:29]
	v_mfma_f32_16x16x32_bf16 v[14:17], v[130:133], v[208:211], v[14:17]
	v_mfma_f32_16x16x32_bf16 v[10:13], v[138:141], v[208:211], v[10:13]
	v_mfma_f32_16x16x32_bf16 v[62:65], v[134:137], v[182:185], v[62:65]
	v_mfma_f32_16x16x32_bf16 v[58:61], v[154:157], v[182:185], v[58:61]
	v_mfma_f32_16x16x32_bf16 v[46:49], v[134:137], v[196:199], v[46:49]
	v_mfma_f32_16x16x32_bf16 v[42:45], v[154:157], v[196:199], v[42:45]
	v_mfma_f32_16x16x32_bf16 v[30:33], v[134:137], v[204:207], v[30:33]
	v_mfma_f32_16x16x32_bf16 v[26:29], v[154:157], v[204:207], v[26:29]
	v_mfma_f32_16x16x32_bf16 v[14:17], v[134:137], v[212:215], v[14:17]
	v_mfma_f32_16x16x32_bf16 v[10:13], v[154:157], v[212:215], v[10:13]
	s_setprio 0
	s_setprio 3
	v_mfma_f32_16x16x32_bf16 v[54:57], v[162:165], v[178:181], v[54:57]
	v_mfma_f32_16x16x32_bf16 v[50:53], v[170:173], v[178:181], v[50:53]
	v_mfma_f32_16x16x32_bf16 v[38:41], v[162:165], v[192:195], v[38:41]
	v_mfma_f32_16x16x32_bf16 v[34:37], v[170:173], v[192:195], v[34:37]
	v_mfma_f32_16x16x32_bf16 v[22:25], v[162:165], v[200:203], v[22:25]
	v_mfma_f32_16x16x32_bf16 v[18:21], v[170:173], v[200:203], v[18:21]
	v_mfma_f32_16x16x32_bf16 v[6:9], v[162:165], v[208:211], v[6:9]
	v_mfma_f32_16x16x32_bf16 v[2:5], v[170:173], v[208:211], v[2:5]
	v_mfma_f32_16x16x32_bf16 v[54:57], v[166:169], v[182:185], v[54:57]
	v_mfma_f32_16x16x32_bf16 v[50:53], v[174:177], v[182:185], v[50:53]
	v_mfma_f32_16x16x32_bf16 v[38:41], v[166:169], v[196:199], v[38:41]
	v_mfma_f32_16x16x32_bf16 v[34:37], v[174:177], v[196:199], v[34:37]
	v_mfma_f32_16x16x32_bf16 v[22:25], v[166:169], v[204:207], v[22:25]
	v_mfma_f32_16x16x32_bf16 v[18:21], v[174:177], v[204:207], v[18:21]
	v_mfma_f32_16x16x32_bf16 v[6:9], v[166:169], v[212:215], v[6:9]
	v_mfma_f32_16x16x32_bf16 v[2:5], v[174:177], v[212:215], v[2:5]
	s_setprio 0
	s_barrier
	s_cmp_ge_i32 s60, s57
	s_mov_b64 s[46:47], s[48:49]
	s_mov_b32 s50, s60
	s_cbranch_scc0 .LBB0_450
